# own counter barrier instead of cg grid sync; phase-2 on half the blocks; silu/sigmoid f32 division sequences replaced by v_rcp_f32+mul (still f32); scan-loop stale vmcnt waits removed
# speedup vs baseline: 1.0375x; 1.0209x over previous
; __device__ __forceinline__ void grid_barrier(unsigned* ctr, const unsigned k) {
;   __syncthreads();
;   if (threadIdx.x == 0) {
;     __hip_atomic_fetch_add(ctr, 1u, __ATOMIC_RELEASE, __HIP_MEMORY_SCOPE_AGENT);
;     const unsigned target = k * gridDim.x;
;     while (__hip_atomic_load(ctr, __ATOMIC_RELAXED, __HIP_MEMORY_SCOPE_AGENT) < target) __builtin_amdgcn_s_sleep(1);
;     __builtin_amdgcn_fence(__ATOMIC_ACQUIRE, "agent");
;   }
;   __syncthreads();
; }
; __global__ void __launch_bounds__(256, 2) mega(Params p) {
;     ...
;   phase0(p, smem); grid.sync();
.LBB0_73:
	s_waitcnt vmcnt(0) lgkmcnt(0)
	s_barrier
	v_cmp_eq_u32_e32 vcc, 0, v218
	s_and_saveexec_b64 s[4:5], vcc
	s_cbranch_execz .LBB0_83
	s_add_u32 s6, s50, 0xf223cb0
	s_addc_u32 s7, s51, 0
	buffer_wbl2 sc1
	s_waitcnt vmcnt(0)
	v_mov_b32_e32 v0, 0
	v_mov_b32_e32 v1, 1
	global_atomic_add v0, v1, s[6:7]
.Lgb0_poll:
	global_load_dword v1, v0, s[6:7] sc1
	s_waitcnt vmcnt(0)
	v_cmp_le_u32_e32 vcc, s3, v1
	s_cbranch_vccnz .Lgb0_done
	s_sleep 1
	s_branch .Lgb0_poll
.Lgb0_done:
	buffer_inv sc1
	s_waitcnt vmcnt(0)

; __device__ __forceinline__ int ltid() { int t = threadIdx.x; asm volatile("" : "+v"(t)); return t; }
; template <bool SIGNAL>
; __device__ __forceinline__ void phase2(const Params& p, unsigned char* smem, const int lo, const int hi, const int worker, const int nworkers) {
;   u16* DX = (u16*)(p.ws + OFF_DX); const u16* HALO = (const u16*)(p.ws + OFF_HALO);
;   const float* BETA = (const float*)(p.ws + OFF_BETA); const float* GG = (const float*)(p.ws + OFF_G);
;   u16* TA = (u16*)(p.ws + OFF_EXTRA);
;   float* sin = (float*)smem;
;   u16* sq = (u16*)(smem + 34304);
;   u16* sk = sq + 64 * 136;
;   u16* svT = sq;
;   float* sgc = (float*)(smem + 34304 + 34816);
;   float* sbeta = sgc + 64;
;   float* sM = (float*)smem;
;   const int tid = ltid(), lane = tid & 63, wave = tid >> 6;
;   const int l31 = lane & 31, hf = lane >> 5;
;   for (int idx2 = lo + worker; idx2 < hi; idx2 += nworkers) {
;     const int bh = idx2 & 15, c = idx2 >> 4; const int it = bh * NCH + c; const int h = bh & 7;
; __device__ __forceinline__ void phase3(const Params& p, unsigned char* smem, unsigned* bar) {
;     ...
;   const bool is_scan = (blockIdx.x < 16);
;   if (is_scan) {
;     f32x16 S[4];
; #pragma unroll
;     for (int d = 0; d < 4; ++d)
; #pragma unroll
;       for (int r = 0; r < 16; ++r) S[d][r] = 0.f;
;     scan_chunked(p, smem, blockIdx.x, S, 0, NCH);
;   } else {
;     phase2<true>(p, smem, P2_SPLIT * 16, NCH * 16, blockIdx.x - 16, gridDim.x - 16);
.LBB0_250:
	s_or_b64 exec, exec, s[4:5]
	v_mov_b32_e32 v220, v218
	v_writelane_b32 v247, s12, 0
	s_cmp_gt_u32 s89, 15
	s_mov_b64 s[4:5], -1
	v_writelane_b32 v247, s13, 1
	s_barrier
	s_cbranch_scc0 .LBB0_311
	s_add_i32 s84, s89, -16
	v_mov_b32_e32 v32, v218
	s_cmpk_gt_i32 s84, 0xf7
	v_writelane_b32 v247, s73, 2
	s_cbranch_scc1 .LBB0_310
	s_load_dwordx2 s[6:7], s[0:1], 0x90
	v_lshlrev_b32_e32 v7, 3, v32
	v_and_b32_e32 v0, 0x78, v7
	v_mov_b32_e32 v35, 0
	v_lshlrev_b32_e32 v34, 1, v0
	s_waitcnt lgkmcnt(0)
	s_add_u32 s85, s6, 0x6090000
	s_addc_u32 s86, s7, 0
	s_add_u32 s2, s6, 0xee1d000
	v_writelane_b32 v247, s2, 3
	s_addc_u32 s2, s7, 0
	v_writelane_b32 v247, s2, 4
	s_add_u32 s2, s6, 0xee9e000
	v_writelane_b32 v247, s2, 5
	s_addc_u32 s2, s7, 0
	v_writelane_b32 v247, s2, 6
	s_add_u32 s2, s6, 0xc5d9000
	v_writelane_b32 v247, s2, 7
	s_addc_u32 s2, s7, 0
	v_lshl_add_u64 v[4:5], s[6:7], 0, v[34:35]
	s_mov_b64 s[12:13], 0xc150000
	v_writelane_b32 v247, s2, 8
	v_lshl_add_u64 v[36:37], v[4:5], 0, s[12:13]
	v_cmp_gt_i32_e64 s[12:13], 64, v32
	v_and_b32_e32 v39, 63, v32
	v_ashrrev_i32_e32 v2, 6, v32
	v_writelane_b32 v247, s12, 9
	v_and_b32_e32 v1, 31, v32
	v_and_b32_e32 v38, 56, v7
	v_writelane_b32 v247, s13, 10
	v_cmp_eq_u32_e64 s[12:13], 0, v32
	v_lshlrev_b32_e32 v7, 5, v2
	v_and_or_b32 v1, v7, 32, v1
	v_writelane_b32 v247, s12, 11
	s_movk_i32 s11, 0x110
	v_ashrrev_i32_e32 v13, 2, v32
	v_writelane_b32 v247, s13, 12
	v_cmp_eq_u32_e64 s[12:13], 0, v39
	s_movk_i32 s8, 0xffe0
	v_bfe_u32 v6, v32, 5, 1
	v_writelane_b32 v247, s12, 13
	v_mad_u32_u24 v11, v1, s11, 16
	v_and_b32_e32 v14, 0xffffffe0, v13
	v_writelane_b32 v247, s13, 14
	v_cmp_gt_u32_e64 s[12:13], 2, v39
	v_bfi_b32 v13, s8, v13, v32
	s_movk_i32 s8, 0xfef4
	v_writelane_b32 v247, s12, 15
	v_mul_u32_u24_e32 v4, 0x118, v39
	v_lshlrev_b32_e32 v5, 3, v39
	v_writelane_b32 v247, s13, 16
	v_cmp_gt_u32_e64 s[12:13], 4, v39
	v_lshl_add_u32 v10, v38, 1, 16
	v_lshlrev_b32_e32 v12, 4, v6
	v_writelane_b32 v247, s12, 17
	v_lshl_or_b32 v20, v6, 2, v14
	v_mad_i32_i24 v6, v1, s8, v11
	v_writelane_b32 v247, s13, 18
	v_cmp_gt_u32_e64 s[12:13], 8, v39
	s_movk_i32 s8, 0x10e
	v_add3_u32 v9, 16, v5, v4
	v_writelane_b32 v247, s12, 19
	v_add_u32_e32 v108, v11, v12
	v_lshlrev_b32_e32 v11, 4, v39
	v_writelane_b32 v247, s13, 20
	v_cmp_gt_u32_e64 s[12:13], 16, v39
	v_mad_u32_u24 v21, v38, s8, v10
	s_movk_i32 s8, 0x42f
	v_writelane_b32 v247, s12, 21
	s_add_i32 s9, 16, 0x10e00
	s_add_i32 s10, 16, 0x10f00
	v_writelane_b32 v247, s13, 22
	v_cmp_gt_u32_e64 s[12:13], 32, v39
	v_sub_u32_e32 v111, v9, v11
	v_lshlrev_b32_e32 v9, 2, v32
	v_writelane_b32 v247, s12, 23
	v_add_u32_e32 v112, s9, v9
	v_add_u32_e32 v113, s10, v9
	v_writelane_b32 v247, s13, 24
	v_cmp_lt_i32_e64 s[12:13], s8, v32
	v_ashrrev_i32_e32 v9, 4, v32
	s_movk_i32 s8, 0x32f
	v_writelane_b32 v247, s12, 25
	v_cmp_gt_i32_e64 s[26:27], 3, v9
	v_lshlrev_b32_e32 v42, 7, v9
	v_writelane_b32 v247, s13, 26
	v_cmp_gt_i32_e64 s[12:13], 51, v9
	v_add_u32_e32 v9, 0x100, v32
	v_ashrrev_i32_e32 v11, 4, v9
	v_writelane_b32 v247, s12, 27
	v_mul_lo_u32 v13, v13, s11
	v_cmp_gt_i32_e64 s[34:35], 3, v11
	v_writelane_b32 v247, s13, 28
	v_cmp_lt_i32_e64 s[12:13], s8, v32
	s_movk_i32 s8, 0x22f
	v_lshlrev_b32_e32 v46, 7, v11
	v_writelane_b32 v247, s12, 29
	v_add3_u32 v109, 16, v13, v12
	v_lshl_add_u32 v8, v0, 2, 16
	v_writelane_b32 v247, s13, 30
	v_cmp_gt_i32_e64 s[12:13], 51, v11
	v_add_u32_e32 v11, 0x200, v32
	v_ashrrev_i32_e32 v12, 4, v11
	v_writelane_b32 v247, s12, 31
	v_cmp_gt_i32_e64 s[40:41], 3, v12
	v_lshlrev_b32_e32 v50, 7, v12
	v_writelane_b32 v247, s13, 32
	v_cmp_lt_i32_e64 s[12:13], s8, v32
	s_movk_i32 s8, 0x12f
	v_ashrrev_i32_e32 v22, 3, v32
	v_writelane_b32 v247, s12, 33
	v_ashrrev_i32_e32 v23, 3, v9
	v_lshlrev_b32_e32 v62, 6, v22
	v_writelane_b32 v247, s13, 34
	v_cmp_gt_i32_e64 s[12:13], 51, v12
	v_add_u32_e32 v12, 0x300, v32
	v_ashrrev_i32_e32 v13, 4, v12
	v_writelane_b32 v247, s12, 35
	v_cmp_gt_i32_e64 s[46:47], 3, v13
	v_lshlrev_b32_e32 v54, 7, v13
	v_writelane_b32 v247, s13, 36
	v_cmp_lt_i32_e64 s[12:13], s8, v32
	s_movk_i32 s8, 0x430
	v_cmp_gt_i32_e64 s[54:55], s8, v32
	v_writelane_b32 v247, s12, 37
	s_movk_i32 s8, 0x330
	v_cmp_gt_i32_e64 s[56:57], s8, v32
	v_writelane_b32 v247, s13, 38
	v_cmp_gt_i32_e64 s[12:13], 51, v13
	v_add_u32_e32 v13, 0x400, v32
	v_ashrrev_i32_e32 v14, 4, v13
	v_writelane_b32 v247, s12, 39
	v_cmp_gt_i32_e64 s[52:53], 3, v14
	v_lshlrev_b32_e32 v58, 7, v14
	v_writelane_b32 v247, s13, 40
	v_cmp_lt_i32_e64 s[12:13], 47, v32
	s_movk_i32 s8, 0x230
	v_lshlrev_b32_e32 v13, 5, v13
	v_writelane_b32 v247, s12, 41
	v_cmp_gt_i32_e64 s[58:59], s8, v32
	s_movk_i32 s8, 0x130
	v_writelane_b32 v247, s13, 42
	v_cmp_gt_i32_e64 s[12:13], 51, v14
	v_lshlrev_b32_e32 v14, 5, v32
	v_and_b32_e32 v14, 0xfffffe00, v14
	v_add_u32_e32 v114, v8, v14
	v_lshlrev_b32_e32 v14, 5, v9
	v_and_b32_e32 v14, 0xfffffe00, v14
	v_add_u32_e32 v115, v8, v14
	v_lshlrev_b32_e32 v14, 5, v11
	v_and_b32_e32 v14, 0xfffffe00, v14
	v_writelane_b32 v247, s12, 43
	v_add_u32_e32 v116, v8, v14
	v_lshlrev_b32_e32 v14, 5, v12
	v_writelane_b32 v247, s13, 44
	v_and_b32_e32 v14, 0xfffffe00, v14
	v_and_b32_e32 v13, 0xfffffe00, v13
	s_movk_i32 s12, 0x90
	v_cmp_gt_i32_e64 s[60:61], s8, v32
	v_add_u32_e32 v117, v8, v14
	v_add_u32_e32 v118, v8, v13
	v_mul_lo_u32 v8, v22, s12
	s_mov_b32 s8, 0x8600
	v_add3_u32 v119, v10, v8, s8
	v_mul_lo_u32 v8, v23, s12
	v_add3_u32 v120, v10, v8, s8
	v_ashrrev_i32_e32 v8, 3, v11
	v_mul_lo_u32 v9, v8, s12
	s_waitcnt vmcnt(6)
	v_lshlrev_b32_e32 v66, 6, v8
	v_ashrrev_i32_e32 v8, 3, v12
	v_add3_u32 v121, v10, v9, s8
	v_mul_lo_u32 v9, v8, s12
	v_cmp_lt_i32_e64 s[12:13], v1, v20
	v_add3_u32 v122, v10, v9, s8
	v_or_b32_e32 v9, 1, v20
	v_writelane_b32 v247, s12, 45
	v_lshlrev_b32_e32 v10, 2, v9
	s_waitcnt vmcnt(5)
; __device__ __forceinline__ u16 f2bf(float f) { return (u16)(cvtpk(f, 0.f) & 0xffffu); }
; template <bool SIGNAL>
; __device__ __forceinline__ void phase2(const Params& p, unsigned char* smem, const int lo, const int hi, const int worker, const int nworkers) {
;     ...
;   for (int idx2 = lo + worker; idx2 < hi; idx2 += nworkers) {
;     const int bh = idx2 & 15, c = idx2 >> 4; const int it = bh * NCH + c; const int h = bh & 7;
;     ...
;       const int j = 32 * tj + l31; const float gcj = sgc[j];
; #pragma unroll
;       for (int r = 0; r < 16; ++r) {
;         const int i = 32 * ti + 8 * (r >> 2) + 4 * hf + (r & 3);
;         const float gci = sgc[i]; const float bi = sbeta[i];
;         const float dec = __expf(gci - gcj);
;         sM[i * 68 + j] = (j < i) ? bi * kk[r] * dec : 0.f;
;         Ag[i * 64 + j] = f2bf((j <= i) ? qk[r] * dec : 0.f);
	v_lshl_or_b32 v72, v9, 6, v1
	v_writelane_b32 v247, s13, 46
	v_cmp_gt_i32_e64 s[12:13], v1, v9
	v_or_b32_e32 v9, 2, v20
	v_add_u32_e32 v125, s9, v10
	v_writelane_b32 v247, s12, 47
	v_add_u32_e32 v126, s10, v10
	v_lshlrev_b32_e32 v10, 2, v9
	v_writelane_b32 v247, s13, 48
	v_cmp_lt_i32_e64 s[12:13], v1, v9
	v_lshl_or_b32 v74, v9, 6, v1
	v_add_u32_e32 v127, s9, v10
	v_writelane_b32 v247, s12, 49
	v_add_u32_e32 v128, s10, v10
	v_lshlrev_b32_e32 v68, 6, v8
	v_writelane_b32 v247, s13, 50
	v_cmp_gt_i32_e64 s[12:13], v1, v9
	v_or_b32_e32 v9, 3, v20
	v_lshlrev_b32_e32 v10, 2, v9
	v_writelane_b32 v247, s12, 51
	s_waitcnt vmcnt(3)
	v_lshl_or_b32 v76, v9, 6, v1
	v_add_u32_e32 v129, s9, v10
	v_writelane_b32 v247, s13, 52
	v_cmp_lt_i32_e64 s[12:13], v1, v9
	v_add_u32_e32 v130, s10, v10
	v_lshlrev_b32_e32 v8, 2, v20
	v_writelane_b32 v247, s12, 53
	v_add_u32_e32 v123, s9, v8
	v_add_u32_e32 v124, s10, v8
	v_writelane_b32 v247, s13, 54
	v_cmp_gt_i32_e64 s[12:13], v1, v9
	v_or_b32_e32 v9, 8, v20
	v_lshlrev_b32_e32 v10, 2, v9
	v_add_u32_e32 v131, s9, v10
	v_add_u32_e32 v132, s10, v10
	v_or_b32_e32 v10, 9, v20
	v_lshlrev_b32_e32 v11, 2, v10
	v_add_u32_e32 v133, s9, v11
	v_add_u32_e32 v134, s10, v11
	v_or_b32_e32 v11, 10, v20
	v_lshlrev_b32_e32 v12, 2, v11
	v_add_u32_e32 v135, s9, v12
	v_add_u32_e32 v136, s10, v12
	v_or_b32_e32 v12, 11, v20
	v_lshlrev_b32_e32 v13, 2, v12
	v_add_u32_e32 v137, s9, v13
	v_add_u32_e32 v138, s10, v13
	v_or_b32_e32 v13, 16, v20
	v_lshlrev_b32_e32 v14, 2, v13
	v_add_u32_e32 v139, s9, v14
	v_add_u32_e32 v140, s10, v14
	v_or_b32_e32 v14, 17, v20
	v_lshlrev_b32_e32 v15, 2, v14
	v_add_u32_e32 v141, s9, v15
	v_add_u32_e32 v142, s10, v15
	v_or_b32_e32 v15, 18, v20
	v_lshlrev_b32_e32 v16, 2, v15
	v_add_u32_e32 v143, s9, v16
	v_add_u32_e32 v144, s10, v16
	v_or_b32_e32 v16, 19, v20
	v_lshlrev_b32_e32 v17, 2, v16
	v_add_u32_e32 v145, s9, v17
	v_add_u32_e32 v146, s10, v17
	v_or_b32_e32 v17, 24, v20
	v_lshlrev_b32_e32 v18, 2, v17
	v_add_u32_e32 v147, s9, v18
	v_add_u32_e32 v148, s10, v18
	v_or_b32_e32 v18, 25, v20
	v_lshlrev_b32_e32 v19, 2, v18
	v_writelane_b32 v247, s12, 55
	v_add_u32_e32 v149, s9, v19
	v_add_u32_e32 v150, s10, v19
	v_or_b32_e32 v19, 26, v20
	v_mul_lo_u32 v8, v20, s11
	v_cmp_gt_i32_e64 s[66:67], v1, v20
	v_lshl_or_b32 v70, v20, 6, v1
	v_writelane_b32 v247, s13, 56
	v_cmp_lt_i32_e64 s[12:13], v1, v9
	v_lshlrev_b32_e32 v24, 2, v19
	v_or_b32_e32 v20, 27, v20
	v_lshl_add_u32 v155, v22, 2, v21
	v_lshlrev_b32_e32 v22, 11, v2
	v_lshlrev_b32_e32 v3, 2, v39
	s_movk_i32 s2, 0x118
	v_lshlrev_b32_e32 v64, 6, v23
	v_writelane_b32 v247, s12, 57
	v_add_u32_e32 v151, s9, v24
	v_add_u32_e32 v152, s10, v24
	v_lshlrev_b32_e32 v24, 2, v20
	v_lshl_add_u32 v156, v23, 2, v21
	v_ashrrev_i32_e32 v23, 31, v22
	v_add_u32_e32 v104, s9, v3
	v_lshl_add_u32 v110, v1, 2, s9
	v_writelane_b32 v247, s13, 58
	v_add_u32_e32 v153, s9, v24
	s_movk_i32 s9, 0xf8
	v_mad_u32_u24 v7, v39, s2, v7
	s_movk_i32 s2, 0x1100
	v_lshlrev_b64 v[22:23], 1, v[22:23]
	v_writelane_b32 v247, s9, 59
	s_add_u32 s9, s6, 0xf223840
	v_add3_u32 v157, v7, v5, s8
	v_mul_lo_u32 v7, v2, s2
	v_or_b32_e32 v22, v22, v3
	v_cmp_gt_u32_e32 vcc, 48, v39
	v_add_u32_e32 v105, s10, v3
	v_lshlrev_b32_e32 v107, 4, v2
	v_writelane_b32 v247, s9, 60
	s_addc_u32 s9, s7, 0
	v_or_b32_e32 v158, v7, v3
	v_lshl_or_b32 v160, v2, 13, v5
	v_lshl_add_u64 v[2:3], s[6:7], 0, v[22:23]
	s_mov_b64 s[6:7], 0x6090200
	v_writelane_b32 v247, s9, 61
	v_lshl_add_u64 v[102:103], v[2:3], 0, s[6:7]
	s_xor_b64 s[6:7], vcc, -1
	v_writelane_b32 v247, s6, 62
	s_add_i32 s2, 16, 0x10efc
	v_sub_u32_e32 v2, v4, v5
	v_writelane_b32 v247, s7, 63
	v_writelane_b32 v246, s2, 0
	v_cmp_gt_i32_e64 s[6:7], v1, v9
	v_lshl_or_b32 v78, v9, 6, v1
	v_lshl_or_b32 v80, v10, 6, v1
	v_writelane_b32 v246, s6, 1
	v_lshl_or_b32 v82, v11, 6, v1
	s_waitcnt vmcnt(2)
; __device__ __forceinline__ u16 f2bf(float f) { return (u16)(cvtpk(f, 0.f) & 0xffffu); }
; template <bool SIGNAL>
; __device__ __forceinline__ void phase2(const Params& p, unsigned char* smem, const int lo, const int hi, const int worker, const int nworkers) {
;     ...
;   for (int idx2 = lo + worker; idx2 < hi; idx2 += nworkers) {
;     const int bh = idx2 & 15, c = idx2 >> 4; const int it = bh * NCH + c; const int h = bh & 7;
;     ...
;       const int j = 32 * tj + l31; const float gcj = sgc[j];
; #pragma unroll
;       for (int r = 0; r < 16; ++r) {
;         const int i = 32 * ti + 8 * (r >> 2) + 4 * hf + (r & 3);
;         const float gci = sgc[i]; const float bi = sbeta[i];
;         const float dec = __expf(gci - gcj);
;         sM[i * 68 + j] = (j < i) ? bi * kk[r] * dec : 0.f;
;         Ag[i * 64 + j] = f2bf((j <= i) ? qk[r] * dec : 0.f);
	v_lshl_or_b32 v84, v12, 6, v1
	v_writelane_b32 v246, s7, 2
	v_cmp_lt_i32_e64 s[6:7], v1, v10
	v_lshl_or_b32 v86, v13, 6, v1
	s_waitcnt vmcnt(1)
	v_lshl_or_b32 v88, v14, 6, v1
	v_writelane_b32 v246, s6, 3
	v_lshl_or_b32 v90, v15, 6, v1
	s_waitcnt vmcnt(0)
	v_lshl_or_b32 v92, v16, 6, v1
	v_writelane_b32 v246, s7, 4
	v_cmp_gt_i32_e64 s[6:7], v1, v10
	v_lshl_or_b32 v94, v17, 6, v1
	v_lshl_or_b32 v96, v18, 6, v1
	v_writelane_b32 v246, s6, 5
	v_lshl_or_b32 v98, v19, 6, v1
	v_lshl_or_b32 v100, v20, 6, v1
	v_writelane_b32 v246, s7, 6
	v_cmp_lt_i32_e64 s[6:7], v1, v11
	v_add_u32_e32 v2, 16, v2
	v_cmp_gt_u32_e64 s[4:5], 64, v32
	v_writelane_b32 v246, s6, 7
	v_mov_b32_e32 v33, v35
	v_lshlrev_b32_e32 v106, 1, v39
	v_writelane_b32 v246, s7, 8
	v_cmp_gt_i32_e64 s[6:7], v1, v11
	v_ashrrev_i32_e32 v41, 31, v32
	v_mov_b32_e32 v40, v32
	v_writelane_b32 v246, s6, 9
	v_add_u32_e32 v44, 0xfffffe80, v42
	v_mov_b32_e32 v45, v35
	v_writelane_b32 v246, s7, 10
	v_cmp_lt_i32_e64 s[6:7], v1, v12
	v_ashrrev_i32_e32 v43, 31, v42
	v_add_u32_e32 v48, 0xfffffe80, v46
	v_writelane_b32 v246, s6, 11
	v_mov_b32_e32 v49, v35
	v_ashrrev_i32_e32 v47, 31, v46
	v_writelane_b32 v246, s7, 12
	v_cmp_gt_i32_e64 s[6:7], v1, v12
	v_add_u32_e32 v52, 0xfffffe80, v50
	v_mov_b32_e32 v53, v35
	v_writelane_b32 v246, s6, 13
	v_ashrrev_i32_e32 v51, 31, v50
	v_add_u32_e32 v56, 0xfffffe80, v54
	v_writelane_b32 v246, s7, 14
	v_cmp_lt_i32_e64 s[6:7], v1, v13
	v_mov_b32_e32 v57, v35
	v_ashrrev_i32_e32 v55, 31, v54
	v_writelane_b32 v246, s6, 15
	v_add_u32_e32 v60, 0xfffffe80, v58
	v_mov_b32_e32 v61, v35
	v_writelane_b32 v246, s7, 16
	v_cmp_gt_i32_e64 s[6:7], v1, v13
	v_ashrrev_i32_e32 v59, 31, v58
	v_cmp_gt_i32_e64 s[62:63], 48, v32
	v_writelane_b32 v246, s6, 17
	v_ashrrev_i32_e32 v63, 31, v62
	v_ashrrev_i32_e32 v65, 31, v64
	v_writelane_b32 v246, s7, 18
	v_cmp_lt_i32_e64 s[6:7], v1, v14
	v_ashrrev_i32_e32 v67, 31, v66
	v_ashrrev_i32_e32 v69, 31, v68
	v_writelane_b32 v246, s6, 19
	v_ashrrev_i32_e32 v71, 31, v70
	v_ashrrev_i32_e32 v73, 31, v72
	v_writelane_b32 v246, s7, 20
	v_cmp_gt_i32_e64 s[6:7], v1, v14
	v_ashrrev_i32_e32 v75, 31, v74
	v_ashrrev_i32_e32 v77, 31, v76
	v_writelane_b32 v246, s6, 21
	v_ashrrev_i32_e32 v79, 31, v78
	v_ashrrev_i32_e32 v81, 31, v80
	v_ashrrev_i32_e32 v83, 31, v82
	v_ashrrev_i32_e32 v85, 31, v84
	v_ashrrev_i32_e32 v87, 31, v86
	v_ashrrev_i32_e32 v89, 31, v88
	v_ashrrev_i32_e32 v91, 31, v90
	v_ashrrev_i32_e32 v93, 31, v92
	v_ashrrev_i32_e32 v95, 31, v94
	v_ashrrev_i32_e32 v97, 31, v96
	v_ashrrev_i32_e32 v99, 31, v98
	v_add_u32_e32 v154, s10, v24
	v_ashrrev_i32_e32 v101, 31, v100
	v_and_b32_e32 v159, 0xffffffc0, v32
	v_add_u32_e32 v161, 0x8600, v2
	v_lshlrev_b32_e32 v34, 1, v0
	s_add_i32 s87, 16, 0xca00
	s_mov_b32 s88, 0x800000
	v_add_u32_e32 v162, v6, v8
	v_mbcnt_hi_u32_b32 v163, -1, v219
	v_mov_b32_e32 v164, 0x300
	v_mov_b32_e32 v165, 0x3db504f3
	s_mov_b32 s2, s89
	v_writelane_b32 v246, s7, 22
	v_cmp_lt_i32_e64 s[10:11], v1, v15
	v_cmp_gt_i32_e64 s[12:13], v1, v15
	v_cmp_lt_i32_e64 s[14:15], v1, v16
	v_cmp_gt_i32_e64 s[16:17], v1, v16
	v_cmp_lt_i32_e64 s[18:19], v1, v17
	v_cmp_gt_i32_e64 s[20:21], v1, v17
	v_cmp_lt_i32_e64 s[6:7], v1, v18
	v_cmp_gt_i32_e64 s[8:9], v1, v18
	v_cmp_lt_i32_e64 s[22:23], v1, v19
	v_cmp_gt_i32_e64 s[24:25], v1, v19
	v_cmp_lt_i32_e64 s[28:29], v1, v20
	v_cmp_gt_i32_e64 s[30:31], v1, v20
	s_mov_b32 s64, 0x358637bd
	s_branch .LBB0_254
.LBB0_253:
	s_or_b64 exec, exec, s[38:39]
	v_readlane_b32 s36, v247, 59
	s_add_i32 s84, s36, s84
	s_addk_i32 s2, 0xf8
	s_cmpk_lt_i32 s84, 0x810
	s_cbranch_scc0 .LBB0_310

; __device__ __forceinline__ unsigned cvtpk(float lo, float hi) { f32x2_t v = {lo, hi}; bf16x2_t b = __builtin_convertvector(v, bf16x2_t); return __builtin_bit_cast(unsigned, b); }
; __device__ __forceinline__ u16 f2bf(float f) { return (u16)(cvtpk(f, 0.f) & 0xffffu); }
; __device__ __forceinline__ float siluf_(float x) { return x / (1.f + __expf(-x)); }
; template <bool SIGNAL>
; __device__ __forceinline__ void phase2(const Params& p, unsigned char* smem, const int lo, const int hi, const int worker, const int nworkers) {
;     ...
;         for (int u = 0; u < 4; ++u) {
;           const int r = wave * 16 + rb * 4 + u;
;           float a0 = 0.f, a1 = 0.f;
; #pragma unroll
;           for (int j = 0; j < 4; ++j) { float2 xv = *(const float2*)(sin + (r + j) * 128 + d0); a0 += w0[j] * xv.x; a1 += w1[j] * xv.y; }
;           y0[u] = siluf_(a0); y1[u] = siluf_(a1);
;         }
;         if (which < 2) {
;           float ss[4];
; #pragma unroll
;           for (int u = 0; u < 4; ++u) ss[u] = y0[u] * y0[u] + y1[u] * y1[u];
; #pragma unroll
;           for (int o = 32; o > 0; o >>= 1) {
; #pragma unroll
;             for (int u = 0; u < 4; ++u) ss[u] += __shfl_xor(ss[u], o);
;           }
; #pragma unroll
;           for (int u = 0; u < 4; ++u) {
;             const int r = wave * 16 + rb * 4 + u;
;             const bool pad = (c == 0 && r < 48);
;             float sc = rsqrtf(ss[u] + 1e-6f) * (which == 0 ? 0.08838834764831845f : 1.f);
;             if (pad) sc = 0.f;
;             unsigned pk = cvtpk(y0[u] * sc, y1[u] * sc);
;             *(unsigned*)(X + r * 128 + d0) = pk;
;             *(unsigned*)((which == 0 ? sq : sk) + r * 136 + d0) = pk;
;           }
;         } else {
; #pragma unroll
;           for (int u = 0; u < 4; ++u) {
;             const int r = wave * 16 + rb * 4 + u;
;             const bool pad = (c == 0 && r < 48);
;             float be = pad ? 0.f : sbeta[r];
;             svT[d0 * 72 + r] = f2bf(y0[u] * be); svT[(d0 + 1) * 72 + r] = f2bf(y1[u] * be);
;           }
.LBB0_279:
	v_add_u32_e32 v28, 16, v20
	ds_read2st64_b64 v[10:13], v28 offset1:1
	ds_read2st64_b64 v[14:17], v28 offset0:2 offset1:3
	v_add_u32_e32 v27, s36, v107
	v_add_u32_e32 v26, 1, v27
	v_add_u32_e32 v23, 2, v27
	s_waitcnt lgkmcnt(1)
	v_pk_fma_f32 v[10:11], v[0:1], v[10:11], 0 op_sel_hi:[1,1,0]
	v_add_u32_e32 v25, 3, v27
	v_pk_fma_f32 v[10:11], v[2:3], v[12:13], v[10:11]
	v_pk_fma_f32 v[12:13], v[0:1], v[12:13], 0 op_sel_hi:[1,1,0]
	s_waitcnt lgkmcnt(0)
	v_pk_fma_f32 v[10:11], v[4:5], v[14:15], v[10:11]
	v_pk_fma_f32 v[12:13], v[2:3], v[14:15], v[12:13]
	v_pk_fma_f32 v[10:11], v[6:7], v[16:17], v[10:11]
	v_pk_fma_f32 v[12:13], v[4:5], v[16:17], v[12:13]
	v_mul_f32_e32 v29, 0xbfb8aa3b, v10
	v_exp_f32_e32 v30, v29
	v_mul_f32_e32 v29, 0xbfb8aa3b, v11
	v_exp_f32_e32 v31, v29
	v_pk_fma_f32 v[14:15], v[0:1], v[14:15], 0 op_sel_hi:[1,1,0]
	v_pk_add_f32 v[30:31], v[30:31], 1.0 op_sel_hi:[1,0]
	s_nop 0
	v_pk_fma_f32 v[14:15], v[2:3], v[16:17], v[14:15]
	v_pk_fma_f32 v[16:17], v[0:1], v[16:17], 0 op_sel_hi:[1,1,0]
	v_rcp_f32_e32 v29, v31
	s_nop 0
	v_mul_f32_e32 v11, v11, v29
	s_nop 0
	ds_read2st64_b64 v[166:169], v28 offset0:4 offset1:5
	v_rcp_f32_e32 v29, v30
	s_nop 0
	v_mul_f32_e32 v10, v10, v29
	s_waitcnt lgkmcnt(0)
	v_pk_fma_f32 v[12:13], v[6:7], v[166:167], v[12:13]
	s_nop 0
	v_mul_f32_e32 v29, 0xbfb8aa3b, v12
	v_exp_f32_e32 v30, v29
	v_mul_f32_e32 v29, 0xbfb8aa3b, v13
	v_exp_f32_e32 v31, v29
	v_pk_fma_f32 v[14:15], v[4:5], v[166:167], v[14:15]
	v_pk_fma_f32 v[16:17], v[2:3], v[166:167], v[16:17]
	v_pk_fma_f32 v[14:15], v[6:7], v[168:169], v[14:15]
	v_pk_add_f32 v[30:31], v[30:31], 1.0 op_sel_hi:[1,0]
	v_pk_fma_f32 v[16:17], v[4:5], v[168:169], v[16:17]
	s_nop 0
	v_rcp_f32_e32 v29, v31
	s_nop 0
	v_mul_f32_e32 v13, v13, v29
	s_nop 0
	v_rcp_f32_e32 v29, v30
	s_nop 0
	v_mul_f32_e32 v12, v12, v29
	v_mul_f32_e32 v29, 0xbfb8aa3b, v14
	v_exp_f32_e32 v30, v29
	v_mul_f32_e32 v29, 0xbfb8aa3b, v15
	v_exp_f32_e32 v31, v29
	s_nop 0
	v_pk_add_f32 v[30:31], v[30:31], 1.0 op_sel_hi:[1,0]
	s_nop 0
	s_nop 0
	v_rcp_f32_e32 v29, v31
	s_nop 0
	v_mul_f32_e32 v15, v15, v29
	s_nop 0
	v_rcp_f32_e32 v29, v30
	s_nop 0
	v_mul_f32_e32 v14, v14, v29
	ds_read_b64 v[28:29], v28 offset:3072
	s_waitcnt lgkmcnt(0)
	v_pk_fma_f32 v[16:17], v[6:7], v[28:29], v[16:17]
	s_nop 0
	v_mul_f32_e32 v28, 0xbfb8aa3b, v16
	v_mul_f32_e32 v29, 0xbfb8aa3b, v17
	v_exp_f32_e32 v28, v28
	v_exp_f32_e32 v29, v29
	s_nop 0
	v_pk_add_f32 v[28:29], v[28:29], 1.0 op_sel_hi:[1,0]
	s_nop 0
	s_nop 0
	v_rcp_f32_e32 v30, v29
	s_nop 0
	v_mul_f32_e32 v17, v17, v30
	s_mov_b64 s[38:39], -1
	v_rcp_f32_e32 v29, v28
	s_nop 0
	v_mul_f32_e32 v16, v16, v29
	s_and_b64 vcc, exec, s[82:83]
	s_cbranch_vccz .LBB0_289
	v_cmp_lt_i32_e32 vcc, 47, v27
	s_xor_b64 s[38:39], s[68:69], -1
	s_or_b64 vcc, s[38:39], vcc
	v_mov_b32_e32 v30, 0
	v_add_u32_e32 v28, 16, v21
	v_mov_b32_e32 v31, 0
	s_and_saveexec_b64 s[42:43], vcc
	v_add_u32_e32 v29, 0x10f00, v28
	ds_read_b32 v31, v29
	s_or_b64 exec, exec, s[42:43]
	s_waitcnt lgkmcnt(0)
	v_mul_f32_e32 v29, v10, v31
	v_mul_f32_e32 v31, v11, v31
	v_cmp_lt_i32_e32 vcc, 47, v26
	v_cvt_pk_bf16_f32 v166, v29, s0
	v_add_u32_e32 v29, 16, v22
	v_cvt_pk_bf16_f32 v31, v31, s0
	s_or_b64 vcc, s[38:39], vcc
	ds_write_b16 v29, v166
	ds_write_b16 v29, v31 offset:144
	s_and_saveexec_b64 s[42:43], vcc
	v_add_u32_e32 v30, 0x10f04, v28
	ds_read_b32 v30, v30
	s_or_b64 exec, exec, s[42:43]
	s_waitcnt lgkmcnt(0)
	v_mul_f32_e32 v31, v12, v30
	v_mul_f32_e32 v30, v13, v30
	v_cvt_pk_bf16_f32 v31, v31, s0
	v_cvt_pk_bf16_f32 v30, v30, s0
	v_cmp_lt_i32_e32 vcc, 47, v23
	ds_write_b16 v29, v31 offset:2
	ds_write_b16 v29, v30 offset:146
	s_or_b64 vcc, s[38:39], vcc
	v_mov_b32_e32 v30, 0
	v_mov_b32_e32 v31, 0
	s_and_saveexec_b64 s[42:43], vcc
	v_add_u32_e32 v31, 0x10f08, v28
	ds_read_b32 v31, v31
	s_or_b64 exec, exec, s[42:43]
	s_waitcnt lgkmcnt(0)
	v_mul_f32_e32 v166, v14, v31
	v_mul_f32_e32 v31, v15, v31
	v_cmp_lt_i32_e32 vcc, 47, v25
	v_cvt_pk_bf16_f32 v166, v166, s0
	v_cvt_pk_bf16_f32 v31, v31, s0
	s_or_b64 s[42:43], s[38:39], vcc
	ds_write_b16 v29, v166 offset:4
	ds_write_b16 v29, v31 offset:148
	s_and_saveexec_b64 s[38:39], s[42:43]
	v_add_u32_e32 v28, 0x10f0c, v28
	ds_read_b32 v30, v28
	s_or_b64 exec, exec, s[38:39]
	s_waitcnt lgkmcnt(0)
	v_mul_f32_e32 v28, v16, v30
	v_cvt_pk_bf16_f32 v28, v28, s0
	ds_write_b16 v29, v28 offset:6
	v_mul_f32_e32 v28, v17, v30
	v_cvt_pk_bf16_f32 v28, v28, s0
	s_mov_b64 s[38:39], 0
	ds_write_b16 v29, v28 offset:150

; __device__ __forceinline__ int ltid() { int t = threadIdx.x; asm volatile("" : "+v"(t)); return t; }
; __device__ __forceinline__ void scan_chunked(const Params& p, unsigned char* smem, int bh, f32x16 (&S)[4], const int c_begin, const int c_end) {
;   u16* DX = (u16*)(p.ws + OFF_DX); const u16* TA = (const u16*)(p.ws + OFF_EXTRA);
;   const int tid = ltid(), lane = tid & 63, wave = tid >> 6;
;   const int l31 = lane & 31, hf = lane >> 5;
;   u16* sk = (u16*)smem;
;   u16* sq = sk + 64 * 136;
;   u16* sT = sq + 64 * 136;
;   u16* sA = sT + 64 * 72;
;   float* sSC = (float*)(sA + 64 * 72);
;   u32x4 pk[4], pq[4], pT[2], pA[2]; uint2 pv[8]; float psc;
;     ...
;       u32x4 id1 = {0u, 0u, 0u, 0u}, id2 = {0u, 0u, 0u, 0u};
;       {
;         const int l15 = l31 & 15;
;         const int jsel = (((l15 >> 2) & 1) == hf) ? (4 * (l15 >> 3) + (l15 & 3)) : -1;
;         const int j1 = (l31 < 16) ? jsel : -1;
;         const int j2 = (l31 >= 16) ? jsel : -1;
;         const unsigned one_lo = 0x3f80u, one_hi = 0x3f800000u;
; #pragma unroll
;         for (int w = 0; w < 4; ++w) {
;           id1[w] = (j1 == 2 * w) ? one_lo : ((j1 == 2 * w + 1) ? one_hi : 0u);
;           id2[w] = (j2 == 2 * w) ? one_lo : ((j2 == 2 * w + 1) ? one_hi : 0u);
;         }
;       }
;       const bf16x8 B1 = __builtin_bit_cast(bf16x8, id1), B2 = __builtin_bit_cast(bf16x8, id2);
.LBB0_311:
	s_andn2_b64 vcc, exec, s[4:5]
	s_cbranch_vccnz .LBB0_320
	v_mov_b32_e32 v152, v218
	s_movk_i32 s4, 0x70
	v_lshlrev_b32_e32 v7, 2, v152
	v_lshlrev_b32_e32 v0, 3, v152
	v_and_b32_e32 v6, 4, v7
	v_and_or_b32 v4, v0, s4, v6
	v_lshrrev_b32_e32 v9, 1, v152
	v_and_b32_e32 v11, 3, v152
	v_bfe_u32 v5, v152, 5, 1
	v_lshl_add_u32 v4, v4, 1, 16
	s_movk_i32 s12, 0x110
	v_and_or_b32 v9, v9, 4, v11
	v_lshrrev_b32_e32 v11, 4, v152
	v_mad_u64_u32 v[158:159], s[10:11], v11, s12, v[4:5]
	v_add_u32_e32 v11, 0x100, v152
	v_lshrrev_b32_e32 v18, 4, v11
	v_mad_u64_u32 v[160:161], s[10:11], v18, s12, v[4:5]
	v_add_u32_e32 v18, 0x200, v152
	v_lshrrev_b32_e32 v18, 4, v18
	v_mad_u64_u32 v[162:163], s[10:11], v18, s12, v[4:5]
	v_add_u32_e32 v18, 0x300, v152
	v_and_b32_e32 v3, 31, v152
	v_and_or_b32 v6, v0, 48, v6
	v_lshl_add_u32 v222, v5, 4, 16
	v_lshrrev_b32_e32 v18, 4, v18
	v_ashrrev_i32_e32 v1, 6, v152
	v_lshl_add_u32 v6, v6, 1, 16
	v_add_u32_e32 v221, 16, v7
	v_mul_u32_u24_e32 v7, 0x110, v3
	v_mad_u32_u24 v223, v3, s12, v222
	v_lshlrev_b32_e32 v8, 7, v3
	v_mad_u64_u32 v[164:165], s[10:11], v18, s12, v[4:5]
	v_lshrrev_b32_e32 v4, 3, v152
	s_movk_i32 s12, 0x90
	v_sub_u32_e32 v224, v223, v8
	v_lshl_or_b32 v8, v1, 5, v3
	v_mad_u64_u32 v[166:167], s[10:11], v4, s12, v[6:7]
	v_lshrrev_b32_e32 v4, 3, v11
	v_lshlrev_b32_e32 v156, 9, v5
	v_add_u32_e32 v10, 0x1000, v8
	v_mad_u64_u32 v[168:169], s[10:11], v4, s12, v[6:7]
	v_or_b32_e32 v4, 0x800, v156
	v_add_u32_e32 v174, v4, v8
	v_add_u32_e32 v176, v4, v10
	v_or_b32_e32 v4, 0x880, v156
	v_lshlrev_b32_e32 v2, 6, v3
	v_add_u32_e32 v178, v4, v8
	v_add_u32_e32 v180, v4, v10
	v_or_b32_e32 v4, 0x900, v156
	v_lshl_or_b32 v154, v1, 11, v2
	v_bfe_u32 v1, v152, 2, 1
	v_add_u32_e32 v182, v4, v8
	v_add_u32_e32 v184, v4, v10
	v_or_b32_e32 v4, 0x980, v156
	v_cmp_eq_u32_e32 vcc, v1, v5
	v_add_u32_e32 v186, v4, v8
	v_add_u32_e32 v188, v4, v10
	v_or_b32_e32 v4, 0xc00, v156
	v_cndmask_b32_e32 v1, -1, v9, vcc
	v_cmp_gt_u32_e32 vcc, 16, v3
	v_add_u32_e32 v190, v4, v8
	v_add_u32_e32 v192, v4, v10
	v_or_b32_e32 v4, 0xc80, v156
	v_cndmask_b32_e32 v9, -1, v1, vcc
	v_cmp_lt_u32_e32 vcc, 15, v3
	v_add_u32_e32 v194, v4, v8
	v_add_u32_e32 v196, v4, v10
	v_or_b32_e32 v4, 0xd00, v156
	v_cndmask_b32_e32 v3, -1, v1, vcc
	v_add_u32_e32 v198, v4, v8
	v_add_u32_e32 v200, v4, v10
	v_or_b32_e32 v4, 0xd80, v156
	v_cmp_eq_u32_e32 vcc, 1, v9
	v_lshlrev_b32_e32 v2, 2, v5
	v_add_u32_e32 v202, v4, v8
	v_add_u32_e32 v204, v4, v10
	v_cndmask_b32_e64 v4, 0, 1.0, vcc
	v_mov_b32_e32 v5, 0x3f80
	v_cmp_ne_u32_e32 vcc, 0, v9
	s_load_dwordx2 s[8:9], s[0:1], 0x90
	s_mov_b32 s7, 0
	v_cndmask_b32_e32 v96, v5, v4, vcc
	v_cmp_eq_u32_e32 vcc, 1, v3
	s_mul_i32 s6, s89, 17
	s_waitcnt lgkmcnt(0)
	s_add_u32 s2, s8, 0x6090000
	v_cndmask_b32_e64 v4, 0, 1.0, vcc
	v_cmp_ne_u32_e32 vcc, 0, v3
	s_addc_u32 s16, s9, 0
	s_add_u32 s17, s8, 0xc5d9000
	v_cndmask_b32_e32 v100, v5, v4, vcc
	v_cmp_eq_u32_e32 vcc, 3, v9
	s_addc_u32 s18, s9, 0
	s_lshl_b64 s[10:11], s[6:7], 2
	v_cndmask_b32_e64 v4, 0, 1.0, vcc
	v_cmp_ne_u32_e32 vcc, 2, v9
	s_add_u32 s6, s8, s10
	v_add_u32_e32 v12, 0x800, v0
	v_cndmask_b32_e32 v97, v5, v4, vcc
	v_cmp_eq_u32_e32 vcc, 3, v3
	v_add_u32_e32 v14, 0x1000, v0
	v_add_u32_e32 v16, 0x1800, v0
	v_cndmask_b32_e64 v4, 0, 1.0, vcc
	v_cmp_ne_u32_e32 vcc, 2, v3
	s_addc_u32 s9, s9, s11
	v_mov_b32_e32 v157, 0
	v_cndmask_b32_e32 v101, v5, v4, vcc
	v_cmp_eq_u32_e32 vcc, 5, v9
	v_ashrrev_i32_e32 v1, 31, v0
	v_ashrrev_i32_e32 v13, 31, v12
	v_cndmask_b32_e64 v4, 0, 1.0, vcc
	v_cmp_ne_u32_e32 vcc, 4, v9
	v_ashrrev_i32_e32 v15, 31, v14
	v_ashrrev_i32_e32 v17, 31, v16
	v_cndmask_b32_e32 v98, v5, v4, vcc
	v_cmp_eq_u32_e32 vcc, 5, v3
	v_add_u32_e32 v170, v156, v8
	v_add_u32_e32 v172, v10, v156
	v_cndmask_b32_e64 v4, 0, 1.0, vcc
	v_cmp_ne_u32_e32 vcc, 4, v3
	s_add_u32 s8, s6, 0xf223840
	v_ashrrev_i32_e32 v11, 31, v10
	v_cndmask_b32_e32 v102, v5, v4, vcc
	v_cmp_eq_u32_e32 vcc, 7, v9
	s_mul_i32 s19, s89, 0x81
	v_ashrrev_i32_e32 v153, 31, v152
	v_cndmask_b32_e64 v4, 0, 1.0, vcc
	v_cmp_ne_u32_e32 vcc, 6, v9
	v_ashrrev_i32_e32 v9, 31, v8
	v_ashrrev_i32_e32 v155, 31, v154
	v_cndmask_b32_e32 v99, v5, v4, vcc
	v_cmp_eq_u32_e32 vcc, 7, v3
	v_cmp_eq_u32_e64 s[4:5], 0, v152
	v_ashrrev_i32_e32 v171, 31, v170
	v_cndmask_b32_e64 v4, 0, 1.0, vcc
	v_cmp_ne_u32_e32 vcc, 6, v3
	v_ashrrev_i32_e32 v173, 31, v172
	v_ashrrev_i32_e32 v175, 31, v174
	v_ashrrev_i32_e32 v177, 31, v176
	v_ashrrev_i32_e32 v179, 31, v178
	v_ashrrev_i32_e32 v181, 31, v180
	v_ashrrev_i32_e32 v183, 31, v182
	v_ashrrev_i32_e32 v185, 31, v184
	v_ashrrev_i32_e32 v187, 31, v186
	v_ashrrev_i32_e32 v189, 31, v188
	v_ashrrev_i32_e32 v191, 31, v190
	v_ashrrev_i32_e32 v193, 31, v192
	v_ashrrev_i32_e32 v195, 31, v194
	v_ashrrev_i32_e32 v197, 31, v196
	v_ashrrev_i32_e32 v199, 31, v198
	v_ashrrev_i32_e32 v201, 31, v200
	v_ashrrev_i32_e32 v203, 31, v202
	v_ashrrev_i32_e32 v205, 31, v204
	v_cndmask_b32_e32 v103, v5, v4, vcc
	s_addc_u32 s9, s9, 0
	v_lshl_add_u64 v[206:207], v[156:157], 0, v[8:9]
	v_lshl_add_u64 v[208:209], v[156:157], 0, v[10:11]
	v_lshlrev_b64 v[210:211], 1, v[0:1]
	v_lshlrev_b64 v[212:213], 1, v[12:13]
	v_lshlrev_b64 v[214:215], 1, v[14:15]
	v_lshlrev_b64 v[216:217], 1, v[16:17]
	s_movk_i32 s6, 0x4000
	v_lshlrev_b32_e32 v156, 1, v2
	s_mov_b64 s[10:11], 0x8000
	s_mov_b32 s20, 0x8000
	v_add_u32_e32 v159, v222, v7
	v_mov_b32_e32 v161, 16
	v_mov_b32_e32 v0, v157
	v_mov_b32_e32 v1, v157
	v_mov_b32_e32 v2, v157
	v_mov_b32_e32 v3, v157
	v_mov_b32_e32 v4, v157
	v_mov_b32_e32 v5, v157
	v_mov_b32_e32 v6, v157
	v_mov_b32_e32 v7, v157
	v_mov_b32_e32 v8, v157
	v_mov_b32_e32 v9, v157
	v_mov_b32_e32 v10, v157
	v_mov_b32_e32 v11, v157
	v_mov_b32_e32 v12, v157
	v_mov_b32_e32 v13, v157
	v_mov_b32_e32 v14, v157
	v_mov_b32_e32 v15, v157
	v_mov_b32_e32 v16, v157
	v_mov_b32_e32 v17, v157
	v_mov_b32_e32 v18, v157
	v_mov_b32_e32 v19, v157
	v_mov_b32_e32 v20, v157
	v_mov_b32_e32 v21, v157
	v_mov_b32_e32 v22, v157
	v_mov_b32_e32 v23, v157
	v_mov_b32_e32 v24, v157
	v_mov_b32_e32 v25, v157
	v_mov_b32_e32 v26, v157
	v_mov_b32_e32 v27, v157
	v_mov_b32_e32 v28, v157
	v_mov_b32_e32 v29, v157
	v_mov_b32_e32 v30, v157
	v_mov_b32_e32 v31, v157
	v_mov_b32_e32 v32, v157
	v_mov_b32_e32 v33, v157
	v_mov_b32_e32 v34, v157
	v_mov_b32_e32 v35, v157
	v_mov_b32_e32 v36, v157
	v_mov_b32_e32 v37, v157
	v_mov_b32_e32 v38, v157
	v_mov_b32_e32 v39, v157
	v_mov_b32_e32 v40, v157
	v_mov_b32_e32 v41, v157
	v_mov_b32_e32 v42, v157
	v_mov_b32_e32 v43, v157
	v_mov_b32_e32 v44, v157
	v_mov_b32_e32 v45, v157
	v_mov_b32_e32 v46, v157
	v_mov_b32_e32 v47, v157
	v_mov_b32_e32 v48, v157
	v_mov_b32_e32 v49, v157
	v_mov_b32_e32 v50, v157
	v_mov_b32_e32 v51, v157
	v_mov_b32_e32 v52, v157
	v_mov_b32_e32 v53, v157
	v_mov_b32_e32 v54, v157
	v_mov_b32_e32 v55, v157
	v_mov_b32_e32 v56, v157
	v_mov_b32_e32 v57, v157
	v_mov_b32_e32 v58, v157
	v_mov_b32_e32 v59, v157
	v_mov_b32_e32 v60, v157
	v_mov_b32_e32 v61, v157
	v_mov_b32_e32 v62, v157
	v_mov_b32_e32 v63, v157
	s_setprio 3
	s_branch .LBB0_316

; __device__ __forceinline__ void scan_chunked(const Params& p, unsigned char* smem, int bh, f32x16 (&S)[4], const int c_begin, const int c_end) {
;     ...
;     {
;       const u16* Xq = DX + ((size_t)(bh * NCH + c) * 3) * 8192; const u16* Xk = Xq + 8192; const u16* Xv = Xk + 8192;
;       const u16* Tg = TA + (size_t)(bh * NCH + c) * 8704; const u16* Ag = Tg + 4096;
; #pragma unroll
;       for (int i = 0; i < 4; ++i) { pk[i] = *(const u32x4*)(Xk + (tid + 256 * i) * 8); pq[i] = *(const u32x4*)(Xq + (tid + 256 * i) * 8); }
; #pragma unroll
;       for (int i = 0; i < 2; ++i) { pT[i] = *(const u32x4*)(Tg + (tid + 256 * i) * 8); pA[i] = *(const u32x4*)(Ag + (tid + 256 * i) * 8); }
;       psc = ((const float*)(Tg + 8192))[tid];
; #pragma unroll
;       for (int i = 0; i < 8; ++i) pv[i] = *(const uint2*)(Xv + (wave * 32 + l31) * 64 + 32 * (i >> 2) + 8 * (i & 3) + 4 * hf);
;     }
; #pragma unroll
;     for (int i = 0; i < 4; ++i) {
;       int idx = tid + 256 * i; int row = idx >> 4, ch = idx & 15; const int po = (ch >> 1) * 16 + (ch & 1) * 4;
;       u16* dk = sk + row * 136 + po; *(uint2*)dk = make_uint2(pk[i].x, pk[i].y); *(uint2*)(dk + 8) = make_uint2(pk[i].z, pk[i].w);
;       u16* dq = sq + row * 136 + po; *(uint2*)dq = make_uint2(pq[i].x, pq[i].y); *(uint2*)(dq + 8) = make_uint2(pq[i].z, pq[i].w);
;     }
; #pragma unroll
;     for (int i = 0; i < 2; ++i) {
;       int idx = tid + 256 * i; int row = idx >> 3, ch = idx & 7; const int po = (ch >> 1) * 16 + (ch & 1) * 4;
;       u16* dt = sT + row * 72 + po; *(uint2*)dt = make_uint2(pT[i].x, pT[i].y); *(uint2*)(dt + 8) = make_uint2(pT[i].z, pT[i].w);
;       u16* da = sA + row * 72 + po; *(uint2*)da = make_uint2(pA[i].x, pA[i].y); *(uint2*)(da + 8) = make_uint2(pA[i].z, pA[i].w);
;     }
;     sSC[tid] = psc;
;     lds_barrier();
;     __builtin_amdgcn_sched_barrier(0);
;     u32x4 yf[4];
;     {
;       f32x16 x0, x1;
; #pragma unroll
;       for (int r = 0; r < 16; ++r) { x0[r] = 0.f; x1[r] = 0.f; }
; #pragma unroll
;       for (int dt = 0; dt < 4; ++dt)
; #pragma unroll
;         for (int s = 0; s < 2; ++s) {
;           u32x4 sb = {cvtpk(S[dt][8 * s + 0], S[dt][8 * s + 1]), cvtpk(S[dt][8 * s + 2], S[dt][8 * s + 3]), cvtpk(S[dt][8 * s + 4], S[dt][8 * s + 5]), cvtpk(S[dt][8 * s + 6], S[dt][8 * s + 7])};
;           const bf16x8 k0f = *(const bf16x8*)(sk + (l31) * 136 + 32 * dt + 16 * s + 8 * hf);
.LBB0_315:
	s_add_i32 s21, s7, s19
	s_mul_i32 s12, s21, 0xc000
	s_mul_hi_u32 s13, s21, 0xc000
	s_add_u32 s12, s2, s12
	s_addc_u32 s13, s16, s13
	s_add_u32 s14, s12, 0x4000
	s_addc_u32 s15, s13, 0
	s_mul_hi_u32 s23, s21, 0x4400
	s_mulk_i32 s21, 0x4400
	s_add_u32 s22, s17, s21
	s_addc_u32 s23, s18, s23
	v_lshl_add_u64 v[64:65], s[14:15], 0, v[210:211]
	v_lshl_add_u64 v[72:73], s[14:15], 0, v[212:213]
	v_lshl_add_u64 v[80:81], s[14:15], 0, v[214:215]
	v_lshl_add_u64 v[88:89], s[14:15], 0, v[216:217]
	s_add_u32 s14, s22, 0x2000
	v_lshl_add_u64 v[68:69], s[12:13], 0, v[210:211]
	v_lshl_add_u64 v[76:77], s[12:13], 0, v[212:213]
	v_lshl_add_u64 v[84:85], s[12:13], 0, v[214:215]
	v_lshl_add_u64 v[92:93], s[12:13], 0, v[216:217]
	s_addc_u32 s15, s23, 0
	v_lshl_add_u64 v[104:105], s[22:23], 0, v[210:211]
	global_load_dwordx4 v[64:67], v[64:65], off
	s_nop 0
	global_load_dwordx4 v[68:71], v[68:69], off
	s_nop 0
	global_load_dwordx4 v[72:75], v[72:73], off
	s_nop 0
	global_load_dwordx4 v[76:79], v[76:77], off
	s_nop 0
	global_load_dwordx4 v[80:83], v[80:81], off
	s_nop 0
	global_load_dwordx4 v[84:87], v[84:85], off
	s_nop 0
	global_load_dwordx4 v[88:91], v[88:89], off
	s_nop 0
	global_load_dwordx4 v[92:95], v[92:93], off
	v_lshl_add_u64 v[106:107], s[14:15], 0, v[210:211]
	global_load_dwordx4 v[120:123], v[104:105], off
	global_load_dwordx4 v[124:127], v[106:107], off
	v_lshl_add_u64 v[104:105], s[22:23], 0, v[212:213]
	v_lshl_add_u64 v[106:107], s[14:15], 0, v[212:213]
	global_load_dwordx4 v[128:131], v[104:105], off
	global_load_dwordx4 v[132:135], v[106:107], off
	v_lshl_add_u64 v[104:105], v[152:153], 2, s[22:23]
	v_add_co_u32_e32 v104, vcc, s6, v104
	v_add_u32_e32 v137, 0x4000, v158
	s_nop 0
	v_addc_co_u32_e32 v105, vcc, 0, v105, vcc
	global_load_dword v136, v[104:105], off
	v_lshl_add_u64 v[104:105], v[154:155], 1, s[12:13]
	v_lshl_add_u64 v[104:105], v[104:105], 0, v[156:157]
	v_lshl_add_u64 v[106:107], v[104:105], 0, s[10:11]
	v_add_co_u32_e32 v104, vcc, s20, v104
	v_add_u32_e32 v138, 0x4000, v160
	s_nop 0
	v_addc_co_u32_e32 v105, vcc, 0, v105, vcc
	global_load_dwordx2 v[118:119], v[104:105], off
	global_load_dwordx2 v[116:117], v[106:107], off offset:64
	global_load_dwordx2 v[112:113], v[106:107], off offset:80
	global_load_dwordx2 v[108:109], v[106:107], off offset:96
	s_nop 0
	global_load_dwordx2 v[104:105], v[106:107], off offset:112
	global_load_dwordx2 v[114:115], v[106:107], off offset:16
	global_load_dwordx2 v[110:111], v[106:107], off offset:32
	s_nop 0
	global_load_dwordx2 v[106:107], v[106:107], off offset:48
	v_add_u32_e32 v139, 0x4000, v162
	v_add_u32_e32 v140, 0x4000, v164
	v_add_u32_e32 v141, 0x8800, v166
	v_add_u32_e32 v142, 0xa800, v166
	v_add_u32_e32 v143, 0x8800, v168
	v_add_u32_e32 v144, 0xa800, v168
	s_waitcnt vmcnt(20)
	ds_write2_b64 v158, v[64:65], v[66:67] offset1:2
	s_waitcnt vmcnt(19)
	ds_write2_b64 v137, v[68:69], v[70:71] offset0:128 offset1:130
	s_waitcnt vmcnt(18)
	ds_write2_b64 v160, v[72:73], v[74:75] offset1:2
	s_waitcnt vmcnt(17)
	ds_write2_b64 v138, v[76:77], v[78:79] offset0:128 offset1:130
	s_waitcnt vmcnt(16)
	ds_write2_b64 v162, v[80:81], v[82:83] offset1:2
	s_waitcnt vmcnt(15)
	ds_write2_b64 v139, v[84:85], v[86:87] offset0:128 offset1:130
	s_waitcnt vmcnt(14)
	ds_write2_b64 v164, v[88:89], v[90:91] offset1:2
	s_waitcnt vmcnt(13)
	ds_write2_b64 v140, v[92:93], v[94:95] offset0:128 offset1:130
	s_waitcnt vmcnt(12)
	ds_write2_b64 v141, v[120:121], v[122:123] offset1:2
	s_waitcnt vmcnt(11)
	ds_write2_b64 v142, v[124:125], v[126:127] offset0:128 offset1:130
	s_waitcnt vmcnt(10)
	ds_write2_b64 v143, v[128:129], v[130:131] offset1:2
	s_waitcnt vmcnt(9)
	ds_write2_b64 v144, v[132:133], v[134:135] offset0:128 offset1:130
	s_waitcnt vmcnt(8)
	ds_write_b32 v221, v136 offset:53248
	s_waitcnt lgkmcnt(0)
	s_barrier
	ds_read_b128 v[64:67], v223
	ds_read_b128 v[128:131], v223 offset:32
	v_cvt_pk_bf16_f32 v120, v48, v49
	v_cvt_pk_bf16_f32 v121, v50, v51
	v_cvt_pk_bf16_f32 v122, v52, v53
	v_cvt_pk_bf16_f32 v123, v54, v55
	ds_read_b128 v[80:83], v223 offset:8704
	ds_read_b128 v[132:135], v223 offset:8736
	v_cvt_pk_bf16_f32 v124, v56, v57
	v_cvt_pk_bf16_f32 v125, v58, v59
	s_waitcnt lgkmcnt(3)
	v_mfma_f32_32x32x16_bf16 v[64:79], v[64:67], v[120:123], 0
	v_cvt_pk_bf16_f32 v126, v60, v61
	v_cvt_pk_bf16_f32 v127, v62, v63
	v_cvt_pk_bf16_f32 v136, v40, v41
	v_cvt_pk_bf16_f32 v137, v42, v43
	v_cvt_pk_bf16_f32 v138, v44, v45
	v_cvt_pk_bf16_f32 v139, v46, v47
	v_cvt_pk_bf16_f32 v148, v24, v25
	s_waitcnt lgkmcnt(1)
	v_mfma_f32_32x32x16_bf16 v[80:95], v[80:83], v[120:123], 0
	ds_read_b128 v[140:143], v223 offset:96
	v_cvt_pk_bf16_f32 v149, v26, v27
	v_cvt_pk_bf16_f32 v150, v28, v29
	v_cvt_pk_bf16_f32 v151, v30, v31
	s_waitcnt vmcnt(7)
	v_lshlrev_b32_e32 v163, 16, v118
	v_and_b32_e32 v118, 0xffff0000, v118
	v_mfma_f32_32x32x16_bf16 v[64:79], v[128:131], v[124:127], v[64:79]
	ds_read_b128 v[128:131], v223 offset:64
	s_waitcnt lgkmcnt(2)
	v_mfma_f32_32x32x16_bf16 v[80:95], v[132:135], v[124:127], v[80:95]
	v_cvt_pk_bf16_f32 v132, v32, v33
	v_cvt_pk_bf16_f32 v133, v34, v35
	v_cvt_pk_bf16_f32 v134, v36, v37
	v_cvt_pk_bf16_f32 v135, v38, v39
	s_waitcnt lgkmcnt(0)
	s_nop 0
	v_mfma_f32_32x32x16_bf16 v[64:79], v[128:131], v[132:135], v[64:79]
	ds_read_b128 v[128:131], v223 offset:8768
	ds_read_b128 v[144:147], v223 offset:8800
	s_waitcnt lgkmcnt(1)
	v_mfma_f32_32x32x16_bf16 v[80:95], v[128:131], v[132:135], v[80:95]
	ds_read_b128 v[128:131], v223 offset:128
	v_mfma_f32_32x32x16_bf16 v[64:79], v[140:143], v[136:139], v[64:79]
	v_cvt_pk_bf16_f32 v140, v16, v17
	v_cvt_pk_bf16_f32 v141, v18, v19
	v_cvt_pk_bf16_f32 v142, v20, v21
	v_cvt_pk_bf16_f32 v143, v22, v23
	s_waitcnt lgkmcnt(1)
; __device__ __forceinline__ unsigned cvtpk(float lo, float hi) { f32x2_t v = {lo, hi}; bf16x2_t b = __builtin_convertvector(v, bf16x2_t); return __builtin_bit_cast(unsigned, b); }
; __device__ __forceinline__ float bflo(unsigned v) { return __uint_as_float(v << 16); }
; __device__ __forceinline__ float bfhi(unsigned v) { return __uint_as_float(v & 0xffff0000u); }
; __device__ __forceinline__ f32x16 mfma32(bf16x8 a, bf16x8 b, f32x16 c) { return __builtin_amdgcn_mfma_f32_32x32x16_bf16(a, b, c, 0, 0, 0); }
; __device__ __forceinline__ void scan_chunked(const Params& p, unsigned char* smem, int bh, f32x16 (&S)[4], const int c_begin, const int c_end) {
;     ...
; #pragma unroll
;       for (int g = 0; g < 4; ++g) {
;         {
;           float4 bg4 = *(const float4*)(sSC + 64 + 8 * g + 4 * hf);
;           uint2 vb = pv[g];
;           yf[(g >> 1)][(g & 1) * 2 + 0] = cvtpk(bflo(vb.x) - bg4.x * x0[4 * g + 0], bfhi(vb.x) - bg4.y * x0[4 * g + 1]);
;           yf[(g >> 1)][(g & 1) * 2 + 1] = cvtpk(bflo(vb.y) - bg4.z * x0[4 * g + 2], bfhi(vb.y) - bg4.w * x0[4 * g + 3]);
;         }
;         {
;           float4 bg4 = *(const float4*)(sSC + 64 + 32 + 8 * g + 4 * hf);
;           uint2 vb = pv[4 + g];
;           yf[2 + (g >> 1)][(g & 1) * 2 + 0] = cvtpk(bflo(vb.x) - bg4.x * x1[4 * g + 0], bfhi(vb.x) - bg4.y * x1[4 * g + 1]);
;           yf[2 + (g >> 1)][(g & 1) * 2 + 1] = cvtpk(bflo(vb.y) - bg4.z * x1[4 * g + 2], bfhi(vb.y) - bg4.w * x1[4 * g + 3]);
;         }
;       }
;     }
;     __builtin_amdgcn_sched_barrier(0);
;     u32x4 vnf[4];
;     {
;       f32x16 v0, v1;
; #pragma unroll
;       for (int r = 0; r < 16; ++r) { v0[r] = 0.f; v1[r] = 0.f; }
; #pragma unroll
;       for (int s = 0; s < 4; ++s) {
;         const bf16x8 t0f = *(const bf16x8*)(sT + (l31) * 72 + 16 * s + 8 * hf);
;         const bf16x8 t1f = *(const bf16x8*)(sT + (32 + l31) * 72 + 16 * s + 8 * hf);
;         v0 = mfma32(t0f, __builtin_bit_cast(bf16x8, yf[s]), v0);
;         v1 = mfma32(t1f, __builtin_bit_cast(bf16x8, yf[s]), v1);
;       }
	v_mfma_f32_32x32x16_bf16 v[80:95], v[144:147], v[136:139], v[80:95]
	ds_read_b128 v[144:147], v223 offset:160
	s_waitcnt lgkmcnt(1)
	v_mfma_f32_32x32x16_bf16 v[64:79], v[128:131], v[140:143], v[64:79]
	ds_read_b128 v[128:131], v223 offset:8832
	ds_read_b128 v[226:229], v223 offset:8864
	s_waitcnt lgkmcnt(1)
	v_mfma_f32_32x32x16_bf16 v[80:95], v[128:131], v[140:143], v[80:95]
	ds_read_b128 v[128:131], v223 offset:192
	v_mfma_f32_32x32x16_bf16 v[64:79], v[144:147], v[148:151], v[64:79]
	v_cvt_pk_bf16_f32 v144, v0, v1
	v_cvt_pk_bf16_f32 v145, v2, v3
	v_cvt_pk_bf16_f32 v146, v4, v5
	v_cvt_pk_bf16_f32 v147, v6, v7
	s_waitcnt lgkmcnt(1)
	v_mfma_f32_32x32x16_bf16 v[80:95], v[226:229], v[148:151], v[80:95]
	ds_read_b128 v[226:229], v223 offset:224
	ds_read_b128 v[230:233], v223 offset:8896
	ds_read_b128 v[234:237], v223 offset:8928
	ds_read_b128 v[238:241], v222 offset:53504
	s_waitcnt lgkmcnt(4)
	v_mfma_f32_32x32x16_bf16 v[64:79], v[128:131], v[144:147], v[64:79]
	v_cvt_pk_bf16_f32 v128, v8, v9
	v_cvt_pk_bf16_f32 v129, v10, v11
	v_cvt_pk_bf16_f32 v130, v12, v13
	v_cvt_pk_bf16_f32 v131, v14, v15
	s_waitcnt lgkmcnt(2)
	v_mfma_f32_32x32x16_bf16 v[80:95], v[230:233], v[144:147], v[80:95]
	v_mfma_f32_32x32x16_bf16 v[64:79], v[226:229], v[128:131], v[64:79]
	ds_read_b128 v[226:229], v222 offset:53536
	s_waitcnt lgkmcnt(2)
	v_mfma_f32_32x32x16_bf16 v[80:95], v[234:237], v[128:131], v[80:95]
	s_waitcnt lgkmcnt(1)
	s_nop 7
	v_fma_f32 v64, -v64, v238, v163
	v_fma_f32 v65, -v65, v239, v118
	v_cvt_pk_bf16_f32 v238, v64, v65
	v_lshlrev_b32_e32 v64, 16, v119
	v_and_b32_e32 v65, 0xffff0000, v119
	v_fma_f32 v64, -v66, v240, v64
	v_fma_f32 v65, -v67, v241, v65
	v_cvt_pk_bf16_f32 v239, v64, v65
	ds_read_b128 v[64:67], v222 offset:53632
	ds_read_b128 v[230:233], v222 offset:53664
	s_waitcnt vmcnt(6)
	v_lshlrev_b32_e32 v118, 16, v116
	s_waitcnt lgkmcnt(1)
	v_fma_f32 v64, -v80, v64, v118
	v_and_b32_e32 v80, 0xffff0000, v116
	v_fma_f32 v65, -v81, v65, v80
	v_cvt_pk_bf16_f32 v116, v64, v65
	v_lshlrev_b32_e32 v64, 16, v117
	v_and_b32_e32 v65, 0xffff0000, v117
	v_fma_f32 v64, -v82, v66, v64
	v_fma_f32 v65, -v83, v67, v65
	v_cvt_pk_bf16_f32 v117, v64, v65
	s_waitcnt vmcnt(2)
	v_lshlrev_b32_e32 v64, 16, v114
	v_and_b32_e32 v65, 0xffff0000, v114
	v_fma_f32 v64, -v68, v226, v64
	v_fma_f32 v65, -v69, v227, v65
	v_cvt_pk_bf16_f32 v240, v64, v65
	v_lshlrev_b32_e32 v64, 16, v115
	v_and_b32_e32 v65, 0xffff0000, v115
	v_fma_f32 v64, -v70, v228, v64
	v_fma_f32 v65, -v71, v229, v65
	v_cvt_pk_bf16_f32 v241, v64, v65
	v_lshlrev_b32_e32 v64, 16, v112
	v_and_b32_e32 v65, 0xffff0000, v112
	s_waitcnt lgkmcnt(0)
	v_fma_f32 v64, -v84, v230, v64
	v_fma_f32 v65, -v85, v231, v65
	v_cvt_pk_bf16_f32 v118, v64, v65
	v_lshlrev_b32_e32 v64, 16, v113
	v_fma_f32 v68, -v86, v232, v64
	ds_read_b128 v[64:67], v222 offset:53568
	v_and_b32_e32 v69, 0xffff0000, v113
	v_fma_f32 v69, -v87, v233, v69
	s_waitcnt vmcnt(1)
	v_lshlrev_b32_e32 v80, 16, v110
	v_cvt_pk_bf16_f32 v119, v68, v69
	ds_read_b128 v[68:71], v222 offset:53600
	s_waitcnt lgkmcnt(1)
	v_fma_f32 v64, -v72, v64, v80
	ds_read_b128 v[80:83], v222 offset:53696
	v_and_b32_e32 v72, 0xffff0000, v110
	v_fma_f32 v65, -v73, v65, v72
	v_cvt_pk_bf16_f32 v110, v64, v65
	v_lshlrev_b32_e32 v64, 16, v111
	v_and_b32_e32 v65, 0xffff0000, v111
	v_fma_f32 v64, -v74, v66, v64
	v_fma_f32 v65, -v75, v67, v65
	v_lshlrev_b32_e32 v72, 16, v108
	v_and_b32_e32 v73, 0xffff0000, v108
	v_cvt_pk_bf16_f32 v111, v64, v65
	ds_read_b128 v[64:67], v222 offset:53728
	s_waitcnt lgkmcnt(1)
	v_fma_f32 v72, -v88, v80, v72
	v_fma_f32 v73, -v89, v81, v73
	v_cvt_pk_bf16_f32 v226, v72, v73
	v_lshlrev_b32_e32 v72, 16, v109
	v_and_b32_e32 v73, 0xffff0000, v109
	v_fma_f32 v72, -v90, v82, v72
	v_fma_f32 v73, -v91, v83, v73
	v_cvt_pk_bf16_f32 v227, v72, v73
	s_waitcnt vmcnt(0)
	v_lshlrev_b32_e32 v72, 16, v106
	v_fma_f32 v68, -v76, v68, v72
	v_and_b32_e32 v72, 0xffff0000, v106
	v_fma_f32 v69, -v77, v69, v72
	v_cvt_pk_bf16_f32 v112, v68, v69
	v_lshlrev_b32_e32 v68, 16, v107
	v_and_b32_e32 v69, 0xffff0000, v107
	v_fma_f32 v68, -v78, v70, v68
	v_fma_f32 v69, -v79, v71, v69
	v_cvt_pk_bf16_f32 v113, v68, v69
	v_lshlrev_b32_e32 v68, 16, v104
	s_waitcnt lgkmcnt(0)
	v_fma_f32 v64, -v92, v64, v68
	v_and_b32_e32 v68, 0xffff0000, v104
	v_fma_f32 v65, -v93, v65, v68
	v_cvt_pk_bf16_f32 v228, v64, v65
	v_lshlrev_b32_e32 v64, 16, v105
	v_and_b32_e32 v65, 0xffff0000, v105
	v_fma_f32 v64, -v94, v66, v64
	v_fma_f32 v65, -v95, v67, v65
	v_cvt_pk_bf16_f32 v229, v64, v65
	ds_read_b128 v[64:67], v224 offset:34816
	ds_read_b128 v[104:107], v224 offset:34848
	ds_read_b128 v[80:83], v224 offset:39424
	ds_read_b128 v[230:233], v224 offset:39456
	s_waitcnt lgkmcnt(3)
	v_mfma_f32_32x32x16_bf16 v[64:79], v[64:67], v[238:241], 0
	s_waitcnt lgkmcnt(1)
	v_mfma_f32_32x32x16_bf16 v[80:95], v[80:83], v[238:241], 0
	v_mfma_f32_32x32x16_bf16 v[64:79], v[104:107], v[110:113], v[64:79]
	s_waitcnt lgkmcnt(0)
	v_mfma_f32_32x32x16_bf16 v[80:95], v[230:233], v[110:113], v[80:95]
	ds_read_b128 v[104:107], v224 offset:34880
	ds_read_b128 v[108:111], v224 offset:34912
	s_waitcnt lgkmcnt(1)
	v_mfma_f32_32x32x16_bf16 v[64:79], v[104:107], v[116:119], v[64:79]
	ds_read_b128 v[104:107], v224 offset:39488
	ds_read_b128 v[112:115], v224 offset:39520
	s_waitcnt lgkmcnt(1)
	v_mfma_f32_32x32x16_bf16 v[80:95], v[104:107], v[116:119], v[80:95]
	v_mfma_f32_32x32x16_bf16 v[64:79], v[108:111], v[226:229], v[64:79]
	s_waitcnt lgkmcnt(0)
; __device__ __forceinline__ unsigned cvtpk(float lo, float hi) { f32x2_t v = {lo, hi}; bf16x2_t b = __builtin_convertvector(v, bf16x2_t); return __builtin_bit_cast(unsigned, b); }
; __device__ __forceinline__ void scan_chunked(const Params& p, unsigned char* smem, int bh, f32x16 (&S)[4], const int c_begin, const int c_end) {
;     ...
; #pragma unroll
;       for (int g = 0; g < 4; ++g) {
;         vnf[(g >> 1)][(g & 1) * 2 + 0] = cvtpk(v0[4 * g + 0], v0[4 * g + 1]);
;         vnf[(g >> 1)][(g & 1) * 2 + 1] = cvtpk(v0[4 * g + 2], v0[4 * g + 3]);
;         vnf[2 + (g >> 1)][(g & 1) * 2 + 0] = cvtpk(v1[4 * g + 0], v1[4 * g + 1]);
;         vnf[2 + (g >> 1)][(g & 1) * 2 + 1] = cvtpk(v1[4 * g + 2], v1[4 * g + 3]);
;       }
;     }
;     __builtin_amdgcn_sched_barrier(0);
;     u16* Oq = DX + ((size_t)(bh * NCH + c) * 3) * 8192;
;     {
;       f32x16 o0, o1;
; #pragma unroll
;       for (int r = 0; r < 16; ++r) { o0[r] = 0.f; o1[r] = 0.f; }
; #pragma unroll
;       for (int dt = 0; dt < 4; ++dt)
; #pragma unroll
;         for (int s = 0; s < 2; ++s) {
;           u32x4 sb = {cvtpk(S[dt][8 * s + 0], S[dt][8 * s + 1]), cvtpk(S[dt][8 * s + 2], S[dt][8 * s + 3]), cvtpk(S[dt][8 * s + 4], S[dt][8 * s + 5]), cvtpk(S[dt][8 * s + 6], S[dt][8 * s + 7])};
;           const bf16x8 q0f = *(const bf16x8*)(sq + (l31) * 136 + 32 * dt + 16 * s + 8 * hf);
;           const bf16x8 q1f = *(const bf16x8*)(sq + (32 + l31) * 136 + 32 * dt + 16 * s + 8 * hf);
;           o0 = mfma32(q0f, __builtin_bit_cast(bf16x8, sb), o0);
;           o1 = mfma32(q1f, __builtin_bit_cast(bf16x8, sb), o1);
;         }
; #pragma unroll
;       for (int g = 0; g < 4; ++g) {
;         float4 e0 = *(const float4*)(sSC + 128 + 8 * g + 4 * hf), e1 = *(const float4*)(sSC + 128 + 32 + 8 * g + 4 * hf);
;         o0[4 * g + 0] *= e0.x; o0[4 * g + 1] *= e0.y; o0[4 * g + 2] *= e0.z; o0[4 * g + 3] *= e0.w;
;         o1[4 * g + 0] *= e1.x; o1[4 * g + 1] *= e1.y; o1[4 * g + 2] *= e1.z; o1[4 * g + 3] *= e1.w;
;       }
; #pragma unroll
;       for (int s = 0; s < 4; ++s) {
;         const bf16x8 a0f = *(const bf16x8*)(sA + (l31) * 72 + 16 * s + 8 * hf);
;         const bf16x8 a1f = *(const bf16x8*)(sA + (32 + l31) * 72 + 16 * s + 8 * hf);
;         o0 = mfma32(a0f, __builtin_bit_cast(bf16x8, vnf[s]), o0);
;         o1 = mfma32(a1f, __builtin_bit_cast(bf16x8, vnf[s]), o1);
;       }
	v_mfma_f32_32x32x16_bf16 v[80:95], v[112:115], v[226:229], v[80:95]
	s_nop 9
	v_cvt_pk_bf16_f32 v116, v64, v65
	v_cvt_pk_bf16_f32 v117, v66, v67
	v_cvt_pk_bf16_f32 v118, v68, v69
	v_cvt_pk_bf16_f32 v119, v70, v71
	v_cvt_pk_bf16_f32 v112, v72, v73
	v_cvt_pk_bf16_f32 v113, v74, v75
	v_cvt_pk_bf16_f32 v114, v76, v77
	v_cvt_pk_bf16_f32 v108, v80, v81
	v_cvt_pk_bf16_f32 v109, v82, v83
	v_cvt_pk_bf16_f32 v110, v84, v85
	v_cvt_pk_bf16_f32 v111, v86, v87
	v_cvt_pk_bf16_f32 v104, v88, v89
	v_cvt_pk_bf16_f32 v105, v90, v91
	v_cvt_pk_bf16_f32 v115, v78, v79
	v_cvt_pk_bf16_f32 v106, v92, v93
	v_cvt_pk_bf16_f32 v107, v94, v95
	ds_read_b128 v[64:67], v223 offset:17408
	ds_read_b128 v[226:229], v223 offset:17440
	ds_read_b128 v[80:83], v223 offset:26112
	ds_read_b128 v[230:233], v223 offset:26144
	s_waitcnt lgkmcnt(3)
	v_mfma_f32_32x32x16_bf16 v[64:79], v[64:67], v[120:123], 0
	s_waitcnt lgkmcnt(1)
	v_mfma_f32_32x32x16_bf16 v[80:95], v[80:83], v[120:123], 0
	v_mfma_f32_32x32x16_bf16 v[64:79], v[226:229], v[124:127], v[64:79]
	s_waitcnt lgkmcnt(0)
	v_mfma_f32_32x32x16_bf16 v[80:95], v[230:233], v[124:127], v[80:95]
	ds_read_b128 v[120:123], v223 offset:17472
	ds_read_b128 v[124:127], v223 offset:17504
	s_waitcnt lgkmcnt(1)
	v_mfma_f32_32x32x16_bf16 v[64:79], v[120:123], v[132:135], v[64:79]
	ds_read_b128 v[120:123], v223 offset:26176
	ds_read_b128 v[226:229], v223 offset:26208
	s_waitcnt lgkmcnt(1)
	v_mfma_f32_32x32x16_bf16 v[80:95], v[120:123], v[132:135], v[80:95]
	v_mfma_f32_32x32x16_bf16 v[64:79], v[124:127], v[136:139], v[64:79]
	ds_read_b128 v[120:123], v223 offset:17536
	ds_read_b128 v[124:127], v223 offset:17568
	s_waitcnt lgkmcnt(2)
	v_mfma_f32_32x32x16_bf16 v[80:95], v[226:229], v[136:139], v[80:95]
	s_waitcnt lgkmcnt(1)
	v_mfma_f32_32x32x16_bf16 v[64:79], v[120:123], v[140:143], v[64:79]
	ds_read_b128 v[120:123], v223 offset:26240
	ds_read_b128 v[132:135], v223 offset:26272
	s_waitcnt lgkmcnt(1)
	v_mfma_f32_32x32x16_bf16 v[80:95], v[120:123], v[140:143], v[80:95]
	v_mfma_f32_32x32x16_bf16 v[64:79], v[124:127], v[148:151], v[64:79]
	ds_read_b128 v[120:123], v223 offset:17600
	ds_read_b128 v[124:127], v223 offset:17632
	s_waitcnt lgkmcnt(2)
	v_mfma_f32_32x32x16_bf16 v[80:95], v[132:135], v[148:151], v[80:95]
	s_waitcnt lgkmcnt(1)
	v_mfma_f32_32x32x16_bf16 v[64:79], v[120:123], v[144:147], v[64:79]
	ds_read_b128 v[120:123], v223 offset:26304
	ds_read_b128 v[132:135], v223 offset:26336
	s_waitcnt lgkmcnt(1)
	v_mfma_f32_32x32x16_bf16 v[80:95], v[120:123], v[144:147], v[80:95]
	v_mfma_f32_32x32x16_bf16 v[64:79], v[124:127], v[128:131], v[64:79]
	ds_read_b128 v[124:127], v222 offset:53824
	ds_read_b128 v[136:139], v222 offset:53856
	ds_read_b128 v[140:143], v222 offset:53760
	ds_read_b128 v[148:151], v222 offset:53792
	ds_read_b128 v[226:229], v222 offset:53888
	ds_read_b128 v[230:233], v222 offset:53920
	s_waitcnt lgkmcnt(4)
	s_nop 4
	v_pk_mul_f32 v[78:79], v[78:79], v[138:139]
	v_mfma_f32_32x32x16_bf16 v[80:95], v[132:135], v[128:131], v[80:95]
	v_mul_f32_e64 v76, v76, v136
	v_mul_f32_e64 v77, v77, v137
	v_mul_f32_e64 v74, v74, v126
	v_mul_f32_e64 v75, v75, v127
	v_mul_f32_e64 v72, v72, v124
	v_mul_f32_e64 v73, v73, v125
	ds_read_b128 v[120:123], v222 offset:53952
	ds_read_b128 v[124:127], v222 offset:53984
	ds_read_b128 v[136:139], v224 offset:44032
	s_waitcnt lgkmcnt(5)
	v_pk_mul_f32 v[70:71], v[70:71], v[150:151]
	v_pk_mul_f32 v[68:69], v[68:69], v[148:149]
	v_pk_mul_f32 v[66:67], v[66:67], v[142:143]
	v_pk_mul_f32 v[64:65], v[64:65], v[140:141]
	s_waitcnt lgkmcnt(1)
	v_pk_mul_f32 v[94:95], v[94:95], v[126:127]
	v_pk_mul_f32 v[92:93], v[92:93], v[124:125]
	ds_read_b128 v[124:127], v224 offset:48640
	ds_read_b128 v[128:131], v224 offset:44064
	s_waitcnt lgkmcnt(2)
	v_mfma_f32_32x32x16_bf16 v[64:79], v[136:139], v[116:119], v[64:79]
	v_mul_f32_e64 v90, v90, v122
	v_mul_f32_e64 v91, v91, v123
	v_mul_f32_e64 v88, v88, v120
	v_mul_f32_e64 v89, v89, v121
	v_mul_f32_e64 v86, v86, v232
	v_mul_f32_e64 v87, v87, v233
	v_pk_mul_f32 v[84:85], v[84:85], v[230:231]
	v_pk_mul_f32 v[82:83], v[82:83], v[228:229]
	v_pk_mul_f32 v[80:81], v[80:81], v[226:227]
	ds_read_b128 v[120:123], v224 offset:48672
	s_waitcnt lgkmcnt(1)
	v_mfma_f32_32x32x16_bf16 v[64:79], v[128:131], v[112:115], v[64:79]
	v_mfma_f32_32x32x16_bf16 v[80:95], v[124:127], v[116:119], v[80:95]
	s_waitcnt lgkmcnt(0)
	v_mfma_f32_32x32x16_bf16 v[80:95], v[120:123], v[112:115], v[80:95]
	ds_read_b128 v[120:123], v224 offset:44096
	ds_read_b128 v[124:127], v224 offset:44128
	s_waitcnt lgkmcnt(1)
	v_mfma_f32_32x32x16_bf16 v[64:79], v[120:123], v[108:111], v[64:79]
	ds_read_b128 v[120:123], v224 offset:48704
	ds_read_b128 v[128:131], v224 offset:48736
	s_waitcnt lgkmcnt(1)
	v_mfma_f32_32x32x16_bf16 v[80:95], v[120:123], v[108:111], v[80:95]
	v_lshl_add_u64 v[120:121], v[170:171], 1, s[12:13]
	v_mfma_f32_32x32x16_bf16 v[64:79], v[124:127], v[104:107], v[64:79]
	s_waitcnt lgkmcnt(0)
; __device__ __forceinline__ unsigned cvtpk(float lo, float hi) { f32x2_t v = {lo, hi}; bf16x2_t b = __builtin_convertvector(v, bf16x2_t); return __builtin_bit_cast(unsigned, b); }
; __device__ __forceinline__ u16 f2bf(float f) { return (u16)(cvtpk(f, 0.f) & 0xffffu); }
; __device__ __forceinline__ void scan_chunked(const Params& p, unsigned char* smem, int bh, f32x16 (&S)[4], const int c_begin, const int c_end) {
;     ...
; #pragma unroll
;       for (int r = 0; r < 16; ++r) {
;         Oq[(8 * (r >> 2) + 4 * hf + (r & 3)) * 128 + wave * 32 + l31] = f2bf(o0[r]);
;         Oq[(32 + 8 * (r >> 2) + 4 * hf + (r & 3)) * 128 + wave * 32 + l31] = f2bf(o1[r]);
;       }
;     }
;     __builtin_amdgcn_sched_barrier(0);
;     const float cd = sSC[128 + 63];
; #pragma unroll
;     for (int dt = 0; dt < 4; ++dt)
; #pragma unroll
;       for (int r = 0; r < 16; ++r) S[dt][r] *= cd;
;     u32x4 vs[4];
; #pragma unroll
;     for (int s = 0; s < 4; ++s) {
;       const float4 e0 = *(const float4*)(sSC + 192 + 16 * s + 4 * hf), e1 = *(const float4*)(sSC + 192 + 16 * s + 8 + 4 * hf);
;       vs[s].x = cvtpk(bflo(vnf[s].x) * e0.x, bfhi(vnf[s].x) * e0.y); vs[s].y = cvtpk(bflo(vnf[s].y) * e0.z, bfhi(vnf[s].y) * e0.w);
;       vs[s].z = cvtpk(bflo(vnf[s].z) * e1.x, bfhi(vnf[s].z) * e1.y); vs[s].w = cvtpk(bflo(vnf[s].w) * e1.z, bfhi(vnf[s].w) * e1.w);
;     }
;     {
;       u32x4 id1 = {0u, 0u, 0u, 0u}, id2 = {0u, 0u, 0u, 0u};
;       {
;         const int l15 = l31 & 15;
;         const int jsel = (((l15 >> 2) & 1) == hf) ? (4 * (l15 >> 3) + (l15 & 3)) : -1;
;         const int j1 = (l31 < 16) ? jsel : -1;
;         const int j2 = (l31 >= 16) ? jsel : -1;
;         const unsigned one_lo = 0x3f80u, one_hi = 0x3f800000u;
; #pragma unroll
;         for (int w = 0; w < 4; ++w) {
;           id1[w] = (j1 == 2 * w) ? one_lo : ((j1 == 2 * w + 1) ? one_hi : 0u);
;           id2[w] = (j2 == 2 * w) ? one_lo : ((j2 == 2 * w + 1) ? one_hi : 0u);
;         }
;       }
;       const bf16x8 B1 = __builtin_bit_cast(bf16x8, id1), B2 = __builtin_bit_cast(bf16x8, id2);
; #pragma unroll
;       for (int dt = 0; dt < 4; ++dt)
; #pragma unroll
;         for (int mt = 0; mt < 2; ++mt) {
;           f32x16 kt;
; #pragma unroll
;           for (int r = 0; r < 16; ++r) kt[r] = 0.f;
;           const u16* k0 = sk + (32 * mt + l31) * 136 + 32 * dt + 8 * hf;
;           kt = mfma32(*(const bf16x8*)(k0), B1, kt);
	v_mfma_f32_32x32x16_bf16 v[80:95], v[128:131], v[104:107], v[80:95]
	s_nop 9
	v_cvt_pk_bf16_f32 v64, v64, s0
	global_store_short v[120:121], v64, off
	v_lshl_add_u64 v[120:121], v[172:173], 1, s[12:13]
	v_cvt_pk_bf16_f32 v66, v66, s0
	v_cvt_pk_bf16_f32 v64, v80, s0
	global_store_short v[120:121], v64, off
	v_cvt_pk_bf16_f32 v80, v65, s0
	v_lshl_add_u64 v[64:65], v[206:207], 1, s[12:13]
	global_store_short v[64:65], v80, off offset:256
	v_cvt_pk_bf16_f32 v120, v81, s0
	v_lshl_add_u64 v[80:81], v[208:209], 1, s[12:13]
	global_store_short v[80:81], v120, off offset:256
	global_store_short v[64:65], v66, off offset:512
	v_cvt_pk_bf16_f32 v66, v82, s0
	global_store_short v[80:81], v66, off offset:512
	v_cvt_pk_bf16_f32 v66, v67, s0
	global_store_short v[64:65], v66, off offset:768
	v_cvt_pk_bf16_f32 v66, v83, s0
	global_store_short v[80:81], v66, off offset:768
	v_cvt_pk_bf16_f32 v66, v68, s0
	global_store_short v[64:65], v66, off offset:2048
	v_cvt_pk_bf16_f32 v66, v84, s0
	global_store_short v[80:81], v66, off offset:2048
	v_cvt_pk_bf16_f32 v66, v69, s0
	global_store_short v[64:65], v66, off offset:2304
	v_cvt_pk_bf16_f32 v66, v85, s0
	global_store_short v[80:81], v66, off offset:2304
	v_cvt_pk_bf16_f32 v66, v70, s0
	global_store_short v[64:65], v66, off offset:2560
	v_cvt_pk_bf16_f32 v66, v86, s0
	global_store_short v[80:81], v66, off offset:2560
	v_cvt_pk_bf16_f32 v66, v71, s0
	global_store_short v[64:65], v66, off offset:2816
	v_cvt_pk_bf16_f32 v64, v87, s0
	global_store_short v[80:81], v64, off offset:2816
	v_cvt_pk_bf16_f32 v66, v72, s0
	v_lshl_add_u64 v[64:65], v[174:175], 1, s[12:13]
	global_store_short v[64:65], v66, off
	v_cvt_pk_bf16_f32 v66, v88, s0
	v_lshl_add_u64 v[64:65], v[176:177], 1, s[12:13]
	global_store_short v[64:65], v66, off
	v_cvt_pk_bf16_f32 v66, v73, s0
	v_lshl_add_u64 v[64:65], v[178:179], 1, s[12:13]
	global_store_short v[64:65], v66, off
	v_cvt_pk_bf16_f32 v66, v89, s0
	v_lshl_add_u64 v[64:65], v[180:181], 1, s[12:13]
	global_store_short v[64:65], v66, off
	v_cvt_pk_bf16_f32 v66, v74, s0
	v_lshl_add_u64 v[64:65], v[182:183], 1, s[12:13]
	global_store_short v[64:65], v66, off
	v_cvt_pk_bf16_f32 v66, v90, s0
	v_lshl_add_u64 v[64:65], v[184:185], 1, s[12:13]
	global_store_short v[64:65], v66, off
	v_cvt_pk_bf16_f32 v66, v75, s0
	v_lshl_add_u64 v[64:65], v[186:187], 1, s[12:13]
	global_store_short v[64:65], v66, off
	v_cvt_pk_bf16_f32 v66, v91, s0
	v_lshl_add_u64 v[64:65], v[188:189], 1, s[12:13]
	global_store_short v[64:65], v66, off
	v_cvt_pk_bf16_f32 v66, v76, s0
	v_lshl_add_u64 v[64:65], v[190:191], 1, s[12:13]
	global_store_short v[64:65], v66, off
	v_cvt_pk_bf16_f32 v66, v92, s0
	v_lshl_add_u64 v[64:65], v[192:193], 1, s[12:13]
	global_store_short v[64:65], v66, off
	v_cvt_pk_bf16_f32 v66, v77, s0
	v_lshl_add_u64 v[64:65], v[194:195], 1, s[12:13]
	global_store_short v[64:65], v66, off
	v_cvt_pk_bf16_f32 v66, v93, s0
	v_lshl_add_u64 v[64:65], v[196:197], 1, s[12:13]
	global_store_short v[64:65], v66, off
	v_cvt_pk_bf16_f32 v66, v78, s0
	v_lshl_add_u64 v[64:65], v[198:199], 1, s[12:13]
	global_store_short v[64:65], v66, off
	v_cvt_pk_bf16_f32 v66, v94, s0
	v_lshl_add_u64 v[64:65], v[200:201], 1, s[12:13]
	global_store_short v[64:65], v66, off
	v_cvt_pk_bf16_f32 v66, v79, s0
	v_lshl_add_u64 v[64:65], v[202:203], 1, s[12:13]
	global_store_short v[64:65], v66, off
	v_cvt_pk_bf16_f32 v66, v95, s0
	v_lshl_add_u64 v[64:65], v[204:205], 1, s[12:13]
	global_store_short v[64:65], v66, off
	ds_read_b32 v92, v161 offset:54012
	ds_read_b128 v[64:67], v159
	ds_read_b128 v[68:71], v222 offset:54016
	ds_read_b128 v[72:75], v222 offset:54048
	v_lshlrev_b32_e32 v76, 16, v116
	v_and_b32_e32 v77, 0xffff0000, v116
	v_lshlrev_b32_e32 v94, 16, v108
	s_waitcnt lgkmcnt(1)
	v_pk_mul_f32 v[68:69], v[68:69], v[76:77]
	v_lshlrev_b32_e32 v76, 16, v112
	v_cvt_pk_bf16_f32 v80, v68, v69
	v_lshlrev_b32_e32 v68, 16, v117
	v_and_b32_e32 v69, 0xffff0000, v117
	v_pk_mul_f32 v[68:69], v[70:71], v[68:69]
	v_and_b32_e32 v77, 0xffff0000, v112
	v_cvt_pk_bf16_f32 v81, v68, v69
	v_lshlrev_b32_e32 v68, 16, v118
	v_and_b32_e32 v69, 0xffff0000, v118
	s_waitcnt lgkmcnt(0)
	v_pk_mul_f32 v[68:69], v[72:73], v[68:69]
	v_and_b32_e32 v95, 0xffff0000, v108
	v_cvt_pk_bf16_f32 v82, v68, v69
	v_lshlrev_b32_e32 v68, 16, v119
	v_and_b32_e32 v69, 0xffff0000, v119
	v_pk_mul_f32 v[72:73], v[74:75], v[68:69]
	ds_read_b128 v[68:71], v222 offset:54080
	v_cvt_pk_bf16_f32 v83, v72, v73
	ds_read_b128 v[72:75], v222 offset:54112
	v_pk_mul_f32 v[62:63], v[62:63], v[92:93] op_sel_hi:[1,0]
	v_pk_mul_f32 v[60:61], v[60:61], v[92:93] op_sel_hi:[1,0]
	s_waitcnt lgkmcnt(1)
	v_pk_mul_f32 v[68:69], v[68:69], v[76:77]
	v_pk_mul_f32 v[58:59], v[58:59], v[92:93] op_sel_hi:[1,0]
	v_cvt_pk_bf16_f32 v84, v68, v69
	v_lshlrev_b32_e32 v68, 16, v113
	v_and_b32_e32 v69, 0xffff0000, v113
	v_pk_mul_f32 v[68:69], v[70:71], v[68:69]
	v_pk_mul_f32 v[56:57], v[56:57], v[92:93] op_sel_hi:[1,0]
	v_cvt_pk_bf16_f32 v85, v68, v69
	v_lshlrev_b32_e32 v68, 16, v114
	v_and_b32_e32 v69, 0xffff0000, v114
	s_waitcnt lgkmcnt(0)
	v_pk_mul_f32 v[68:69], v[72:73], v[68:69]
	v_pk_mul_f32 v[54:55], v[54:55], v[92:93] op_sel_hi:[1,0]
	v_cvt_pk_bf16_f32 v86, v68, v69
	v_lshlrev_b32_e32 v68, 16, v115
	v_and_b32_e32 v69, 0xffff0000, v115
	v_pk_mul_f32 v[68:69], v[74:75], v[68:69]
	ds_read_b128 v[88:91], v222 offset:54144
	ds_read_b128 v[112:115], v159 offset:32
	v_cvt_pk_bf16_f32 v87, v68, v69
	v_mfma_f32_32x32x16_bf16 v[64:79], v[64:67], v[96:99], 0
	ds_read_b128 v[116:119], v222 offset:54176
	s_waitcnt lgkmcnt(2)
; __device__ __forceinline__ float bflo(unsigned v) { return __uint_as_float(v << 16); }
; __device__ __forceinline__ void scan_chunked(const Params& p, unsigned char* smem, int bh, f32x16 (&S)[4], const int c_begin, const int c_end) {
;     ...
;     const float cd = sSC[128 + 63];
; #pragma unroll
;     for (int dt = 0; dt < 4; ++dt)
; #pragma unroll
;       for (int r = 0; r < 16; ++r) S[dt][r] *= cd;
;     u32x4 vs[4];
; #pragma unroll
;     for (int s = 0; s < 4; ++s) {
;       const float4 e0 = *(const float4*)(sSC + 192 + 16 * s + 4 * hf), e1 = *(const float4*)(sSC + 192 + 16 * s + 8 + 4 * hf);
;       vs[s].x = cvtpk(bflo(vnf[s].x) * e0.x, bfhi(vnf[s].x) * e0.y); vs[s].y = cvtpk(bflo(vnf[s].y) * e0.z, bfhi(vnf[s].y) * e0.w);
;       vs[s].z = cvtpk(bflo(vnf[s].z) * e1.x, bfhi(vnf[s].z) * e1.y); vs[s].w = cvtpk(bflo(vnf[s].w) * e1.z, bfhi(vnf[s].w) * e1.w);
;     }
;     {
;       u32x4 id1 = {0u, 0u, 0u, 0u}, id2 = {0u, 0u, 0u, 0u};
;       {
;         const int l15 = l31 & 15;
;         const int jsel = (((l15 >> 2) & 1) == hf) ? (4 * (l15 >> 3) + (l15 & 3)) : -1;
;         const int j1 = (l31 < 16) ? jsel : -1;
;         const int j2 = (l31 >= 16) ? jsel : -1;
;         const unsigned one_lo = 0x3f80u, one_hi = 0x3f800000u;
; #pragma unroll
;         for (int w = 0; w < 4; ++w) {
;           id1[w] = (j1 == 2 * w) ? one_lo : ((j1 == 2 * w + 1) ? one_hi : 0u);
;           id2[w] = (j2 == 2 * w) ? one_lo : ((j2 == 2 * w + 1) ? one_hi : 0u);
;         }
;       }
;       const bf16x8 B1 = __builtin_bit_cast(bf16x8, id1), B2 = __builtin_bit_cast(bf16x8, id2);
; #pragma unroll
;       for (int dt = 0; dt < 4; ++dt)
; #pragma unroll
;         for (int mt = 0; mt < 2; ++mt) {
;           f32x16 kt;
; #pragma unroll
;           for (int r = 0; r < 16; ++r) kt[r] = 0.f;
;           const u16* k0 = sk + (32 * mt + l31) * 136 + 32 * dt + 8 * hf;
;           kt = mfma32(*(const bf16x8*)(k0), B1, kt);
;           kt = mfma32(*(const bf16x8*)(k0 + 16), B2, kt);
; #pragma unroll
;           for (int s2 = 0; s2 < 2; ++s2) {
;             u32x4 af = {cvtpk(kt[8 * s2 + 0], kt[8 * s2 + 1]), cvtpk(kt[8 * s2 + 2], kt[8 * s2 + 3]), cvtpk(kt[8 * s2 + 4], kt[8 * s2 + 5]), cvtpk(kt[8 * s2 + 6], kt[8 * s2 + 7])};
;             S[dt] = mfma32(__builtin_bit_cast(bf16x8, af), __builtin_bit_cast(bf16x8, vs[2 * mt + s2]), S[dt]);
	v_mul_f32_e64 v88, v88, v94
	v_mul_f32_e64 v89, v89, v95
	v_lshlrev_b32_e32 v94, 16, v109
	v_and_b32_e32 v95, 0xffff0000, v109
	v_pk_mul_f32 v[52:53], v[52:53], v[92:93] op_sel_hi:[1,0]
	v_pk_mul_f32 v[50:51], v[50:51], v[92:93] op_sel_hi:[1,0]
	v_pk_mul_f32 v[48:49], v[48:49], v[92:93] op_sel_hi:[1,0]
	s_waitcnt lgkmcnt(1)
	v_mfma_f32_32x32x16_bf16 v[64:79], v[112:115], v[100:103], v[64:79]
	v_cvt_pk_bf16_f32 v88, v88, v89
	ds_read_b128 v[112:115], v159 offset:8736
	v_mul_f32_e64 v46, v46, v92
	v_mul_f32_e64 v47, v47, v92
	v_mul_f32_e64 v44, v44, v92
	v_mul_f32_e64 v45, v45, v92
	v_pk_mul_f32 v[42:43], v[42:43], v[92:93] op_sel_hi:[1,0]
	v_pk_mul_f32 v[40:41], v[40:41], v[92:93] op_sel_hi:[1,0]
	v_pk_mul_f32 v[38:39], v[38:39], v[92:93] op_sel_hi:[1,0]
	s_nop 2
	v_cvt_pk_bf16_f32 v64, v64, v65
	v_cvt_pk_bf16_f32 v65, v66, v67
	v_cvt_pk_bf16_f32 v66, v68, v69
	v_cvt_pk_bf16_f32 v67, v70, v71
	v_pk_mul_f32 v[68:69], v[90:91], v[94:95]
	v_lshlrev_b32_e32 v94, 16, v104
	v_cvt_pk_bf16_f32 v89, v68, v69
	v_lshlrev_b32_e32 v68, 16, v110
	v_and_b32_e32 v69, 0xffff0000, v110
	v_mfma_f32_32x32x16_bf16 v[48:63], v[64:67], v[80:83], v[48:63]
	v_cvt_pk_bf16_f32 v64, v72, v73
	v_lshlrev_b32_e32 v72, 16, v111
	v_and_b32_e32 v73, 0xffff0000, v111
	ds_read_b128 v[108:111], v222 offset:54208
	s_waitcnt lgkmcnt(2)
	v_pk_mul_f32 v[68:69], v[116:117], v[68:69]
	v_cvt_pk_bf16_f32 v65, v74, v75
	v_cvt_pk_bf16_f32 v90, v68, v69
	ds_read_b128 v[68:71], v159 offset:8704
	v_cvt_pk_bf16_f32 v66, v76, v77
	v_cvt_pk_bf16_f32 v67, v78, v79
	v_and_b32_e32 v95, 0xffff0000, v104
	s_waitcnt lgkmcnt(1)
	v_pk_mul_f32 v[94:95], v[108:109], v[94:95]
	v_mfma_f32_32x32x16_bf16 v[48:63], v[64:67], v[84:87], v[48:63]
	v_mul_f32_e64 v64, v118, v72
	v_mul_f32_e64 v65, v119, v73
	ds_read_b128 v[116:119], v222 offset:54240
	v_cvt_pk_bf16_f32 v91, v64, v65
	v_cvt_pk_bf16_f32 v104, v94, v95
	v_lshlrev_b32_e32 v94, 16, v105
	v_and_b32_e32 v95, 0xffff0000, v105
	v_pk_mul_f32 v[94:95], v[110:111], v[94:95]
	s_waitcnt lgkmcnt(1)
	v_mfma_f32_32x32x16_bf16 v[64:79], v[68:71], v[96:99], 0
	v_cvt_pk_bf16_f32 v105, v94, v95
	ds_read_b128 v[108:111], v159 offset:96
	v_mul_f32_e64 v36, v36, v92
	v_mul_f32_e64 v37, v37, v92
	v_mul_f32_e64 v34, v34, v92
	v_mul_f32_e64 v35, v35, v92
	v_pk_mul_f32 v[32:33], v[32:33], v[92:93] op_sel_hi:[1,0]
	v_pk_mul_f32 v[30:31], v[30:31], v[92:93] op_sel_hi:[1,0]
	v_pk_mul_f32 v[28:29], v[28:29], v[92:93] op_sel_hi:[1,0]
	v_mfma_f32_32x32x16_bf16 v[64:79], v[112:115], v[100:103], v[64:79]
	v_mul_f32_e64 v26, v26, v92
	v_mul_f32_e64 v27, v27, v92
	v_mul_f32_e64 v24, v24, v92
	v_mul_f32_e64 v25, v25, v92
	v_mul_f32_e64 v22, v22, v92
	v_mul_f32_e64 v23, v23, v92
	v_pk_mul_f32 v[20:21], v[20:21], v[92:93] op_sel_hi:[1,0]
	v_pk_mul_f32 v[18:19], v[18:19], v[92:93] op_sel_hi:[1,0]
	v_pk_mul_f32 v[16:17], v[16:17], v[92:93] op_sel_hi:[1,0]
	v_pk_mul_f32 v[14:15], v[14:15], v[92:93] op_sel_hi:[1,0]
	s_nop 1
	v_cvt_pk_bf16_f32 v64, v64, v65
	v_cvt_pk_bf16_f32 v65, v66, v67
	v_cvt_pk_bf16_f32 v66, v68, v69
	v_cvt_pk_bf16_f32 v67, v70, v71
	v_lshlrev_b32_e32 v68, 16, v106
	v_and_b32_e32 v69, 0xffff0000, v106
	v_mfma_f32_32x32x16_bf16 v[48:63], v[64:67], v[88:91], v[48:63]
	v_cvt_pk_bf16_f32 v64, v72, v73
	v_cvt_pk_bf16_f32 v65, v74, v75
	v_cvt_pk_bf16_f32 v66, v76, v77
	v_cvt_pk_bf16_f32 v67, v78, v79
	s_waitcnt lgkmcnt(1)
	v_pk_mul_f32 v[68:69], v[116:117], v[68:69]
	v_pk_mul_f32 v[12:13], v[12:13], v[92:93] op_sel_hi:[1,0]
	v_cvt_pk_bf16_f32 v106, v68, v69
	v_lshlrev_b32_e32 v68, 16, v107
	v_and_b32_e32 v69, 0xffff0000, v107
	v_pk_mul_f32 v[68:69], v[118:119], v[68:69]
	v_pk_mul_f32 v[10:11], v[10:11], v[92:93] op_sel_hi:[1,0]
	v_cvt_pk_bf16_f32 v107, v68, v69
	v_pk_mul_f32 v[8:9], v[8:9], v[92:93] op_sel_hi:[1,0]
	v_pk_mul_f32 v[6:7], v[6:7], v[92:93] op_sel_hi:[1,0]
	v_mfma_f32_32x32x16_bf16 v[48:63], v[64:67], v[104:107], v[48:63]
	ds_read_b128 v[64:67], v159 offset:64
	v_mul_f32_e64 v4, v4, v92
	v_mul_f32_e64 v5, v5, v92
	v_mul_f32_e64 v2, v2, v92
	v_mul_f32_e64 v3, v3, v92
	v_pk_mul_f32 v[0:1], v[0:1], v[92:93] op_sel_hi:[1,0]
	s_add_i32 s7, s7, 1
	s_cmpk_eq_i32 s7, 0x81
	s_waitcnt lgkmcnt(0)
; __device__ __forceinline__ unsigned cvtpk(float lo, float hi) { f32x2_t v = {lo, hi}; bf16x2_t b = __builtin_convertvector(v, bf16x2_t); return __builtin_bit_cast(unsigned, b); }
; __device__ __forceinline__ f32x16 mfma32(bf16x8 a, bf16x8 b, f32x16 c) { return __builtin_amdgcn_mfma_f32_32x32x16_bf16(a, b, c, 0, 0, 0); }
; __device__ __forceinline__ void lds_barrier() { asm volatile("s_waitcnt lgkmcnt(0)\n\ts_barrier" ::: "memory"); }
; __device__ __forceinline__ void scan_chunked(const Params& p, unsigned char* smem, int bh, f32x16 (&S)[4], const int c_begin, const int c_end) {
;     ...
; #pragma unroll
;       for (int dt = 0; dt < 4; ++dt)
; #pragma unroll
;         for (int mt = 0; mt < 2; ++mt) {
;           f32x16 kt;
; #pragma unroll
;           for (int r = 0; r < 16; ++r) kt[r] = 0.f;
;           const u16* k0 = sk + (32 * mt + l31) * 136 + 32 * dt + 8 * hf;
;           kt = mfma32(*(const bf16x8*)(k0), B1, kt);
;           kt = mfma32(*(const bf16x8*)(k0 + 16), B2, kt);
; #pragma unroll
;           for (int s2 = 0; s2 < 2; ++s2) {
;             u32x4 af = {cvtpk(kt[8 * s2 + 0], kt[8 * s2 + 1]), cvtpk(kt[8 * s2 + 2], kt[8 * s2 + 3]), cvtpk(kt[8 * s2 + 4], kt[8 * s2 + 5]), cvtpk(kt[8 * s2 + 6], kt[8 * s2 + 7])};
;             S[dt] = mfma32(__builtin_bit_cast(bf16x8, af), __builtin_bit_cast(bf16x8, vs[2 * mt + s2]), S[dt]);
;           }
;         }
;     }
;     lds_barrier();
;   }
	v_mfma_f32_32x32x16_bf16 v[64:79], v[64:67], v[96:99], 0
	v_mfma_f32_32x32x16_bf16 v[64:79], v[108:111], v[100:103], v[64:79]
	ds_read_b128 v[108:111], v159 offset:8800
	s_nop 10
	v_cvt_pk_bf16_f32 v64, v64, v65
	v_cvt_pk_bf16_f32 v65, v66, v67
	v_cvt_pk_bf16_f32 v66, v68, v69
	v_cvt_pk_bf16_f32 v67, v70, v71
	s_nop 1
	v_mfma_f32_32x32x16_bf16 v[32:47], v[64:67], v[80:83], v[32:47]
	v_cvt_pk_bf16_f32 v64, v72, v73
	v_cvt_pk_bf16_f32 v65, v74, v75
	v_cvt_pk_bf16_f32 v66, v76, v77
	v_cvt_pk_bf16_f32 v67, v78, v79
	s_nop 1
	v_mfma_f32_32x32x16_bf16 v[32:47], v[64:67], v[84:87], v[32:47]
	ds_read_b128 v[64:67], v159 offset:8768
	s_waitcnt lgkmcnt(0)
	v_mfma_f32_32x32x16_bf16 v[64:79], v[64:67], v[96:99], 0
	v_mfma_f32_32x32x16_bf16 v[64:79], v[108:111], v[100:103], v[64:79]
	ds_read_b128 v[108:111], v159 offset:160
	s_nop 10
	v_cvt_pk_bf16_f32 v64, v64, v65
	v_cvt_pk_bf16_f32 v65, v66, v67
	v_cvt_pk_bf16_f32 v66, v68, v69
	v_cvt_pk_bf16_f32 v67, v70, v71
	s_nop 1
	v_mfma_f32_32x32x16_bf16 v[32:47], v[64:67], v[88:91], v[32:47]
	v_cvt_pk_bf16_f32 v64, v72, v73
	v_cvt_pk_bf16_f32 v65, v74, v75
	v_cvt_pk_bf16_f32 v66, v76, v77
	v_cvt_pk_bf16_f32 v67, v78, v79
	s_nop 1
	v_mfma_f32_32x32x16_bf16 v[32:47], v[64:67], v[104:107], v[32:47]
	ds_read_b128 v[64:67], v159 offset:128
	s_waitcnt lgkmcnt(0)
	v_mfma_f32_32x32x16_bf16 v[64:79], v[64:67], v[96:99], 0
	v_mfma_f32_32x32x16_bf16 v[64:79], v[108:111], v[100:103], v[64:79]
	ds_read_b128 v[108:111], v159 offset:8864
	s_nop 10
	v_cvt_pk_bf16_f32 v64, v64, v65
	v_cvt_pk_bf16_f32 v65, v66, v67
	v_cvt_pk_bf16_f32 v66, v68, v69
	v_cvt_pk_bf16_f32 v67, v70, v71
	s_nop 1
	v_mfma_f32_32x32x16_bf16 v[16:31], v[64:67], v[80:83], v[16:31]
	v_cvt_pk_bf16_f32 v64, v72, v73
	v_cvt_pk_bf16_f32 v65, v74, v75
	v_cvt_pk_bf16_f32 v66, v76, v77
	v_cvt_pk_bf16_f32 v67, v78, v79
	s_nop 1
	v_mfma_f32_32x32x16_bf16 v[16:31], v[64:67], v[84:87], v[16:31]
	ds_read_b128 v[64:67], v159 offset:8832
	s_waitcnt lgkmcnt(0)
	v_mfma_f32_32x32x16_bf16 v[64:79], v[64:67], v[96:99], 0
	v_mfma_f32_32x32x16_bf16 v[64:79], v[108:111], v[100:103], v[64:79]
	ds_read_b128 v[108:111], v159 offset:224
	s_nop 10
	v_cvt_pk_bf16_f32 v64, v64, v65
	v_cvt_pk_bf16_f32 v65, v66, v67
	v_cvt_pk_bf16_f32 v66, v68, v69
	v_cvt_pk_bf16_f32 v67, v70, v71
	s_nop 1
	v_mfma_f32_32x32x16_bf16 v[16:31], v[64:67], v[88:91], v[16:31]
	v_cvt_pk_bf16_f32 v64, v72, v73
	v_cvt_pk_bf16_f32 v65, v74, v75
	v_cvt_pk_bf16_f32 v66, v76, v77
	v_cvt_pk_bf16_f32 v67, v78, v79
	s_nop 1
	v_mfma_f32_32x32x16_bf16 v[16:31], v[64:67], v[104:107], v[16:31]
	ds_read_b128 v[64:67], v159 offset:192
	s_waitcnt lgkmcnt(0)
	v_mfma_f32_32x32x16_bf16 v[64:79], v[64:67], v[96:99], 0
	v_mfma_f32_32x32x16_bf16 v[64:79], v[108:111], v[100:103], v[64:79]
	s_nop 11
	v_cvt_pk_bf16_f32 v64, v64, v65
	v_cvt_pk_bf16_f32 v65, v66, v67
	v_cvt_pk_bf16_f32 v66, v68, v69
	v_cvt_pk_bf16_f32 v67, v70, v71
	s_nop 1
	v_mfma_f32_32x32x16_bf16 v[0:15], v[64:67], v[80:83], v[0:15]
	v_cvt_pk_bf16_f32 v64, v72, v73
	v_cvt_pk_bf16_f32 v65, v74, v75
	v_cvt_pk_bf16_f32 v66, v76, v77
	v_cvt_pk_bf16_f32 v67, v78, v79
	ds_read_b128 v[80:83], v159 offset:8928
	s_nop 0
	v_mfma_f32_32x32x16_bf16 v[0:15], v[64:67], v[84:87], v[0:15]
	ds_read_b128 v[64:67], v159 offset:8896
	s_waitcnt lgkmcnt(0)
	s_barrier
	s_waitcnt lgkmcnt(0)
	v_mfma_f32_32x32x16_bf16 v[64:79], v[64:67], v[96:99], 0
	v_mfma_f32_32x32x16_bf16 v[64:79], v[80:83], v[100:103], v[64:79]
	s_nop 11
	v_cvt_pk_bf16_f32 v64, v64, v65
	v_cvt_pk_bf16_f32 v65, v66, v67
	v_cvt_pk_bf16_f32 v66, v68, v69
	v_cvt_pk_bf16_f32 v67, v70, v71
	s_nop 1
	v_mfma_f32_32x32x16_bf16 v[0:15], v[64:67], v[88:91], v[0:15]
	v_cvt_pk_bf16_f32 v64, v72, v73
	v_cvt_pk_bf16_f32 v65, v74, v75
	v_cvt_pk_bf16_f32 v66, v76, v77
	v_cvt_pk_bf16_f32 v67, v78, v79
	s_nop 1
	v_mfma_f32_32x32x16_bf16 v[0:15], v[64:67], v[104:107], v[0:15]
	s_cbranch_scc1 .LBB0_320

; __device__ __forceinline__ void phase3(const Params& p, unsigned char* smem, unsigned* bar) {
;     ...
;   int* cnt = (int*)(p.ws + OFF_CTL);
;   const float lam = ((const float*)(p.ws + OFF_CTL))[16];
;   const int myq = blockIdx.x & 7;
;   for (int qq = 0; qq < 8; ++qq) {
;     const int q = (myq + qq) & 7;
.LBB0_320:
	s_setprio 0
	s_load_dwordx2 s[36:37], s[0:1], 0x90
	s_load_dwordx2 s[6:7], s[0:1], 0x40
	s_nop 8
	v_mov_b32_e32 v0, 0xf223000
	v_mbcnt_hi_u32_b32 v194, -1, v219
	s_mov_b32 s9, 0
	s_waitcnt lgkmcnt(0)
	global_load_dword v176, v0, s[36:37] offset:64
	s_add_u32 s35, s36, 0xf223000
	s_addc_u32 s38, s37, 0
	s_add_u32 s39, s36, 0x2010000
	s_addc_u32 s40, s37, 0
	v_and_b32_e32 v0, 64, v194
	s_add_u32 s41, s36, 0x4050000
	v_cmp_eq_u32_e64 s[4:5], 0, v220
	v_mov_b32_e32 v179, 0
	s_movk_i32 s2, 0xff
	s_movk_i32 s20, 0x4080
	s_mov_b32 s21, 0x8000
	s_mov_b32 s22, 0x10000
	s_mov_b32 s23, 0x18000
	s_movk_i32 s24, 0x110
	s_movk_i32 s25, 0x90
	s_mov_b32 s26, 0x20000
	s_mov_b32 s27, 0x28000
	s_mov_b32 s28, 0x30000
	s_mov_b32 s29, 0x38000
	s_mov_b32 s30, 0xf149f2ca
	s_movk_i32 s31, 0x210
	v_mov_b32_e32 v196, 0x358637bd
	s_mov_b32 s34, 0x800000
	v_mov_b32_e32 v197, 0xf149f2ca
	v_xor_b32_e32 v198, 32, v194
	v_add_u32_e32 v195, 64, v0
	s_addc_u32 s42, s37, 0
	s_mov_b32 s43, 0
	s_waitcnt vmcnt(0)
	v_mov_b32_e32 v177, v176
	s_branch .LBB0_322

; __device__ __forceinline__ float sigmoidf_(float x) { return 1.f / (1.f + __expf(-x)); }
; __device__ __forceinline__ uint4 pack8(float4 a, float4 b) { uint4 o; o.x = cvtpk(a.x, a.y); o.y = cvtpk(a.z, a.w); o.z = cvtpk(b.x, b.y); o.w = cvtpk(b.z, b.w); return o; }
; template <class Epi>
; __device__ __forceinline__ void epilogue_rows(f32x16 (&acc)[2][2], int m0, int n0, unsigned char* smem, Epi epi) {
;     ...
;   for (int it = 0; it < 8; ++it) {
;     int idx = tid + 256 * it; int r = idx >> 4, c8 = (idx & 15) * 8;
;     float4 a = *(const float4*)(sC + r * 132 + c8), b = *(const float4*)(sC + r * 132 + c8 + 4);
;     epi(m0 + r, n0 + c8, a, b);
; __device__ __forceinline__ void phase4(const Params& p, unsigned char* smem) {
;     ...
;       epilogue_rows(acc, m0, n0, smem, [&](int m, int n, float4 a, float4 b) {
;         int col = n - 8208; u16* dst = col < 1024 ? SGA + col : SGD + (col - 1024);
;         a.x = sigmoidf_(a.x); a.y = sigmoidf_(a.y); a.z = sigmoidf_(a.z); a.w = sigmoidf_(a.w);
;         b.x = sigmoidf_(b.x); b.y = sigmoidf_(b.y); b.z = sigmoidf_(b.z); b.w = sigmoidf_(b.w);
;         *(uint4*)(dst + (size_t)m * 1024) = pack8(a, b);
;       });
.LBB0_376:
	s_nop 0
	v_add_u32_e32 v68, s68, v65
	v_ashrrev_i32_e32 v69, 4, v68
	v_add_u32_e32 v68, 0x100, v68
	v_mad_u64_u32 v[72:73], s[4:5], v69, s56, v[64:65]
	v_add_u32_e32 v76, s66, v69
	v_ashrrev_i32_e32 v78, 4, v68
	ds_read_b128 v[68:71], v72
	ds_read_b128 v[72:75], v72 offset:16
	v_ashrrev_i32_e32 v77, 31, v76
	v_mad_u64_u32 v[80:81], s[4:5], v78, s56, v[64:65]
	v_add_u32_e32 v84, s66, v78
	v_lshlrev_b64 v[86:87], 11, v[76:77]
	ds_read_b128 v[76:79], v80
	ds_read_b128 v[80:83], v80 offset:16
	s_waitcnt lgkmcnt(3)
	v_mul_f32_e32 v68, 0xbfb8aa3b, v68
	v_mul_f32_e32 v69, 0xbfb8aa3b, v69
	v_exp_f32_e32 v68, v68
	v_exp_f32_e32 v69, v69
	v_mul_f32_e32 v70, 0xbfb8aa3b, v70
	v_mul_f32_e32 v71, 0xbfb8aa3b, v71
	s_waitcnt lgkmcnt(1)
	v_mul_f32_e32 v76, 0xbfb8aa3b, v76
	v_mul_f32_e32 v77, 0xbfb8aa3b, v77
	v_exp_f32_e32 v70, v70
	v_exp_f32_e32 v71, v71
	v_exp_f32_e32 v76, v76
	v_exp_f32_e32 v77, v77
	v_mul_f32_e32 v72, 0xbfb8aa3b, v72
	v_mul_f32_e32 v73, 0xbfb8aa3b, v73
	v_mul_f32_e32 v78, 0xbfb8aa3b, v78
	v_mul_f32_e32 v79, 0xbfb8aa3b, v79
	v_exp_f32_e32 v72, v72
	v_exp_f32_e32 v73, v73
	v_exp_f32_e32 v78, v78
	v_exp_f32_e32 v79, v79
	v_pk_add_f32 v[68:69], v[68:69], 1.0 op_sel_hi:[1,0]
	v_mul_f32_e32 v74, 0xbfb8aa3b, v74
	v_mul_f32_e32 v75, 0xbfb8aa3b, v75
	s_waitcnt lgkmcnt(0)
	v_mul_f32_e32 v80, 0xbfb8aa3b, v80
	v_mul_f32_e32 v81, 0xbfb8aa3b, v81
	v_exp_f32_e32 v74, v74
	v_exp_f32_e32 v75, v75
	v_exp_f32_e32 v80, v80
	v_exp_f32_e32 v81, v81
	v_pk_add_f32 v[70:71], v[70:71], 1.0 op_sel_hi:[1,0]
	v_pk_add_f32 v[76:77], v[76:77], 1.0 op_sel_hi:[1,0]
	v_mul_f32_e32 v82, 0xbfb8aa3b, v82
	v_mul_f32_e32 v83, 0xbfb8aa3b, v83
	v_exp_f32_e32 v82, v82
	v_exp_f32_e32 v83, v83
	v_pk_add_f32 v[72:73], v[72:73], 1.0 op_sel_hi:[1,0]
	v_pk_add_f32 v[78:79], v[78:79], 1.0 op_sel_hi:[1,0]
	v_pk_add_f32 v[74:75], v[74:75], 1.0 op_sel_hi:[1,0]
	v_pk_add_f32 v[80:81], v[80:81], 1.0 op_sel_hi:[1,0]
	v_pk_add_f32 v[82:83], v[82:83], 1.0 op_sel_hi:[1,0]
	v_rcp_f32_e32 v69, v69
	s_nop 0
	v_rcp_f32_e32 v68, v68
	s_nop 0
	v_rcp_f32_e32 v71, v71
	s_nop 0
	v_cvt_pk_bf16_f32 v68, v68, v69
	v_rcp_f32_e32 v69, v70
	s_nop 0
	v_rcp_f32_e32 v70, v73
	s_nop 0
	v_cvt_pk_bf16_f32 v69, v69, v71
	v_rcp_f32_e32 v71, v72
	s_nop 0
	v_rcp_f32_e32 v72, v75
	s_nop 0
	v_cvt_pk_bf16_f32 v70, v71, v70
	v_rcp_f32_e32 v71, v74
	s_nop 0
	v_lshl_add_u64 v[86:87], v[66:67], 0, v[86:87]
	v_cvt_pk_bf16_f32 v71, v71, v72
	v_rcp_f32_e32 v72, v77
	s_nop 0
	global_store_dwordx4 v[86:87], v[68:71], off
	s_nop 1
	v_rcp_f32_e32 v68, v76
	s_nop 0
	v_rcp_f32_e32 v69, v79
	s_nop 0
	v_cvt_pk_bf16_f32 v68, v68, v72
	v_rcp_f32_e32 v70, v78
	s_nop 0
	v_cvt_pk_bf16_f32 v69, v70, v69
	v_rcp_f32_e32 v70, v80
	s_nop 0
	v_ashrrev_i32_e32 v85, 31, v84
	v_rcp_f32_e32 v71, v81
	s_nop 0
	s_addk_i32 s68, 0x200
	v_lshlrev_b64 v[84:85], 11, v[84:85]
	v_rcp_f32_e32 v72, v83
	s_nop 0
	v_cvt_pk_bf16_f32 v70, v70, v71
	v_rcp_f32_e32 v71, v82
	s_nop 0
	s_cmpk_lg_i32 s68, 0x800
	v_lshl_add_u64 v[84:85], v[66:67], 0, v[84:85]
	v_cvt_pk_bf16_f32 v71, v71, v72
	global_store_dwordx4 v[84:85], v[68:71], off
	s_cbranch_scc1 .LBB0_376
	s_barrier
	s_mov_b64 s[4:5], 0

; __device__ __forceinline__ float bflo(unsigned v) { return __uint_as_float(v << 16); }
; __device__ __forceinline__ float bfhi(unsigned v) { return __uint_as_float(v & 0xffff0000u); }
; __device__ __forceinline__ float siluf_(float x) { return x / (1.f + __expf(-x)); }
; __device__ __forceinline__ uint4 pack8(float4 a, float4 b) { uint4 o; o.x = cvtpk(a.x, a.y); o.y = cvtpk(a.z, a.w); o.z = cvtpk(b.x, b.y); o.w = cvtpk(b.z, b.w); return o; }
; __device__ __forceinline__ void phase4(const Params& p, unsigned char* smem) {
;     ...
;       epilogue_rows(acc, m0, n0, smem, [&](int m, int n, float4 a, float4 b) {
;         int col = n - 7168; int h = col >> 7, d = col & 127;
;         int bb = m >> 13, t = m & 8191; int bh = bb * 8 + h; int pp = t + 64;
;         uint4* ptr = (uint4*)(DX + (((size_t)(bh * NCH + (pp >> 6))) * 3) * 8192 + (pp & 63) * 128 + d);
;         uint4 o = *ptr;
;         float o0 = bflo(o.x), o1 = bfhi(o.x), o2 = bflo(o.y), o3 = bfhi(o.y), o4 = bflo(o.z), o5 = bfhi(o.z), o6 = bflo(o.w), o7 = bfhi(o.w);
;         float sq = o0 * o0 + o1 * o1 + o2 * o2 + o3 * o3 + o4 * o4 + o5 * o5 + o6 * o6 + o7 * o7;
;         sq += __shfl_xor(sq, 1); sq += __shfl_xor(sq, 2); sq += __shfl_xor(sq, 4); sq += __shfl_xor(sq, 8);
;         float rs = rsqrtf(sq * (1.f / 128.f) + 1e-6f);
;         float4 w0 = *(const float4*)(p.dn_norm_w + d), w1 = *(const float4*)(p.dn_norm_w + d + 4);
;         a.x = o0 * rs * w0.x * siluf_(a.x); a.y = o1 * rs * w0.y * siluf_(a.y); a.z = o2 * rs * w0.z * siluf_(a.z); a.w = o3 * rs * w0.w * siluf_(a.w);
;         b.x = o4 * rs * w1.x * siluf_(b.x); b.y = o5 * rs * w1.y * siluf_(b.y); b.z = o6 * rs * w1.z * siluf_(b.z); b.w = o7 * rs * w1.w * siluf_(b.w);
;         *ptr = pack8(a, b);
.LBB0_380:
	v_add_u32_e32 v72, s68, v81
	v_ashrrev_i32_e32 v74, 4, v72
	v_add_u32_e32 v75, 0x100, v72
	v_mad_u64_u32 v[72:73], s[4:5], v74, s56, v[80:81]
	v_add_u32_e32 v73, s66, v74
	v_and_b32_e32 v76, 0x1fc0, v73
	v_ashrrev_i32_e32 v77, 10, v73
	global_load_dwordx4 v[64:67], v[82:83], off offset:16
	global_load_dwordx4 v[68:71], v[82:83], off
	ds_read_b128 v[100:103], v72
	ds_read_b128 v[104:107], v72 offset:16
	v_and_b32_e32 v94, -8, v77
	v_add_u32_e32 v95, 64, v76
	v_add_u32_e32 v109, v94, v88
	v_lshrrev_b32_e32 v94, 6, v95
	v_mov_b64_e32 v[86:87], s[42:43]
	v_lshlrev_b32_e32 v74, 8, v74
	v_mad_u64_u32 v[94:95], s[4:5], v109, s58, v[94:95]
	v_ashrrev_i32_e32 v75, 4, v75
	v_and_b32_e32 v96, 0x3f00, v74
	v_mad_i64_i32 v[94:95], s[4:5], v94, s59, v[86:87]
	v_mov_b32_e32 v85, v97
	v_mad_u64_u32 v[72:73], s[4:5], v75, s56, v[80:81]
	v_lshl_add_u64 v[94:95], v[94:95], 0, v[96:97]
	v_add_u32_e32 v73, s66, v75
	s_waitcnt lgkmcnt(1)
	v_mul_f32_e32 v116, 0xbfb8aa3b, v103
	v_mul_f32_e32 v117, 0xbfb8aa3b, v100
	v_mul_f32_e32 v118, 0xbfb8aa3b, v101
	s_waitcnt lgkmcnt(0)
	v_mul_f32_e32 v119, 0xbfb8aa3b, v106
	v_lshl_add_u64 v[94:95], v[94:95], 0, v[84:85]
	v_lshlrev_b32_e32 v93, 8, v75
	v_and_b32_e32 v98, 0x1fc0, v73
	v_ashrrev_i32_e32 v108, 10, v73
	ds_read_b128 v[76:79], v72
	ds_read_b128 v[72:75], v72 offset:16
	v_exp_f32_e32 v121, v116
	v_exp_f32_e32 v122, v117
	v_exp_f32_e32 v123, v118
	v_exp_f32_e32 v124, v119
	global_load_dwordx4 v[116:119], v[94:95], off
	v_and_b32_e32 v108, -8, v108
	v_add_u32_e32 v98, 64, v98
	v_add_u32_e32 v108, v108, v88
	v_lshrrev_b32_e32 v98, 6, v98
	v_mad_u64_u32 v[108:109], s[4:5], v108, s58, v[98:99]
	v_mul_f32_e32 v98, 0xbfb8aa3b, v104
	v_mul_f32_e32 v109, 0xbfb8aa3b, v105
	v_mad_i64_i32 v[86:87], s[4:5], v108, s59, v[86:87]
	v_and_b32_e32 v96, 0x3f00, v93
	v_exp_f32_e32 v108, v98
	v_exp_f32_e32 v109, v109
	v_mul_f32_e32 v115, 0xbfb8aa3b, v102
	v_lshl_add_u64 v[86:87], v[86:87], 0, v[96:97]
	s_waitcnt lgkmcnt(0)
	v_mul_f32_e32 v93, 0xbfb8aa3b, v72
	v_mul_f32_e32 v96, 0xbfb8aa3b, v73
	v_exp_f32_e32 v120, v115
	v_exp_f32_e32 v126, v93
	v_exp_f32_e32 v127, v96
	v_mul_f32_e32 v98, 0xbfb8aa3b, v78
	v_mul_f32_e32 v115, 0xbfb8aa3b, v79
	v_exp_f32_e32 v128, v98
	v_exp_f32_e32 v129, v115
	v_pk_add_f32 v[108:109], v[108:109], 1.0 op_sel_hi:[1,0]
	v_mul_f32_e32 v125, 0xbfb8aa3b, v107
	v_mul_f32_e32 v130, 0xbfb8aa3b, v76
	v_mul_f32_e32 v131, 0xbfb8aa3b, v77
	v_lshl_add_u64 v[86:87], v[86:87], 0, v[84:85]
	v_exp_f32_e32 v125, v125
	v_exp_f32_e32 v130, v130
	v_exp_f32_e32 v131, v131
	v_pk_add_f32 v[120:121], v[120:121], 1.0 op_sel_hi:[1,0]
	v_pk_add_f32 v[126:127], v[126:127], 1.0 op_sel_hi:[1,0]
	v_mul_f32_e32 v132, 0xbfb8aa3b, v74
	v_mul_f32_e32 v133, 0xbfb8aa3b, v75
	v_exp_f32_e32 v132, v132
	v_exp_f32_e32 v133, v133
	v_pk_add_f32 v[122:123], v[122:123], 1.0 op_sel_hi:[1,0]
	v_pk_add_f32 v[128:129], v[128:129], 1.0 op_sel_hi:[1,0]
	v_pk_add_f32 v[124:125], v[124:125], 1.0 op_sel_hi:[1,0]
	v_pk_add_f32 v[130:131], v[130:131], 1.0 op_sel_hi:[1,0]
	v_pk_add_f32 v[132:133], v[132:133], 1.0 op_sel_hi:[1,0]
	v_rcp_f32_e32 v85, v109
	s_nop 0
	v_mul_f32_e32 v105, v105, v85
	v_rcp_f32_e32 v85, v108
	s_nop 0
	v_mul_f32_e32 v104, v104, v85
	v_rcp_f32_e32 v85, v121
	s_nop 0
	v_mul_f32_e32 v103, v103, v85
	v_rcp_f32_e32 v85, v120
	s_nop 0
	v_mul_f32_e32 v102, v102, v85
	v_rcp_f32_e32 v85, v123
	s_nop 0
	v_mul_f32_e32 v101, v101, v85
	v_rcp_f32_e32 v85, v122
	s_nop 0
	v_mul_f32_e32 v100, v100, v85
	s_waitcnt vmcnt(0)
	v_lshlrev_b32_e32 v108, 16, v116
	v_and_b32_e32 v109, 0xffff0000, v116
	v_rcp_f32_e32 v85, v125
	s_nop 0
	v_mul_f32_e32 v107, v107, v85
	v_lshlrev_b32_e32 v116, 16, v117
	v_and_b32_e32 v117, 0xffff0000, v117
	v_pk_mul_f32 v[136:137], v[108:109], v[108:109]
	v_rcp_f32_e32 v85, v124
	s_nop 0
	v_mul_f32_e32 v106, v106, v85
	v_pk_mul_f32 v[134:135], v[116:117], v[116:117]
	v_add_f32_e32 v85, v136, v137
	v_lshlrev_b32_e32 v120, 16, v118
	v_and_b32_e32 v121, 0xffff0000, v118
	v_add_f32_e32 v85, v85, v134
	v_pk_mul_f32 v[124:125], v[120:121], v[120:121]
	v_add_f32_e32 v85, v135, v85
	v_lshlrev_b32_e32 v118, 16, v119
	v_and_b32_e32 v119, 0xffff0000, v119
	v_add_f32_e32 v85, v124, v85
	v_pk_mul_f32 v[122:123], v[118:119], v[118:119]
	v_add_f32_e32 v85, v125, v85
	v_add_f32_e32 v85, v122, v85
	v_add_f32_e32 v85, v123, v85
	ds_bpermute_b32 v93, v89, v85
	s_waitcnt lgkmcnt(0)
; __device__ __forceinline__ float bflo(unsigned v) { return __uint_as_float(v << 16); }
; __device__ __forceinline__ float bfhi(unsigned v) { return __uint_as_float(v & 0xffff0000u); }
; __device__ __forceinline__ float siluf_(float x) { return x / (1.f + __expf(-x)); }
; __device__ __forceinline__ uint4 pack8(float4 a, float4 b) { uint4 o; o.x = cvtpk(a.x, a.y); o.y = cvtpk(a.z, a.w); o.z = cvtpk(b.x, b.y); o.w = cvtpk(b.z, b.w); return o; }
; __device__ __forceinline__ void phase4(const Params& p, unsigned char* smem) {
;     ...
;       epilogue_rows(acc, m0, n0, smem, [&](int m, int n, float4 a, float4 b) {
;         int col = n - 7168; int h = col >> 7, d = col & 127;
;         int bb = m >> 13, t = m & 8191; int bh = bb * 8 + h; int pp = t + 64;
;         uint4* ptr = (uint4*)(DX + (((size_t)(bh * NCH + (pp >> 6))) * 3) * 8192 + (pp & 63) * 128 + d);
;         uint4 o = *ptr;
;         float o0 = bflo(o.x), o1 = bfhi(o.x), o2 = bflo(o.y), o3 = bfhi(o.y), o4 = bflo(o.z), o5 = bfhi(o.z), o6 = bflo(o.w), o7 = bfhi(o.w);
;         float sq = o0 * o0 + o1 * o1 + o2 * o2 + o3 * o3 + o4 * o4 + o5 * o5 + o6 * o6 + o7 * o7;
;         sq += __shfl_xor(sq, 1); sq += __shfl_xor(sq, 2); sq += __shfl_xor(sq, 4); sq += __shfl_xor(sq, 8);
;         float rs = rsqrtf(sq * (1.f / 128.f) + 1e-6f);
;         float4 w0 = *(const float4*)(p.dn_norm_w + d), w1 = *(const float4*)(p.dn_norm_w + d + 4);
;         a.x = o0 * rs * w0.x * siluf_(a.x); a.y = o1 * rs * w0.y * siluf_(a.y); a.z = o2 * rs * w0.z * siluf_(a.z); a.w = o3 * rs * w0.w * siluf_(a.w);
;         b.x = o4 * rs * w1.x * siluf_(b.x); b.y = o5 * rs * w1.y * siluf_(b.y); b.z = o6 * rs * w1.z * siluf_(b.z); b.w = o7 * rs * w1.w * siluf_(b.w);
;         *ptr = pack8(a, b);
	v_add_f32_e32 v85, v85, v93
	ds_bpermute_b32 v93, v90, v85
	s_waitcnt lgkmcnt(0)
	v_add_f32_e32 v85, v85, v93
	ds_bpermute_b32 v93, v91, v85
	s_waitcnt lgkmcnt(0)
	v_add_f32_e32 v85, v85, v93
	ds_bpermute_b32 v93, v92, v85
	s_waitcnt lgkmcnt(0)
	v_add_f32_e32 v85, v85, v93
	v_fmamk_f32 v85, v85, 0x3c000000, v110
	v_mul_f32_e32 v93, 0x4b800000, v85
	v_cmp_gt_f32_e32 vcc, s60, v85
	s_nop 1
	v_cndmask_b32_e32 v85, v85, v93, vcc
	v_rsq_f32_e32 v85, v85
	s_nop 0
	v_mul_f32_e32 v93, 0x45800000, v85
	v_cndmask_b32_e32 v96, v85, v93, vcc
	v_pk_mul_f32 v[108:109], v[96:97], v[108:109] op_sel_hi:[0,1]
	v_pk_mul_f32 v[116:117], v[96:97], v[116:117] op_sel_hi:[0,1]
	v_pk_mul_f32 v[120:121], v[96:97], v[120:121] op_sel_hi:[0,1]
	v_pk_mul_f32 v[118:119], v[96:97], v[118:119] op_sel_hi:[0,1]
	v_pk_mul_f32 v[68:69], v[68:69], v[108:109]
	v_pk_mul_f32 v[70:71], v[70:71], v[116:117]
	v_pk_mul_f32 v[64:65], v[64:65], v[120:121]
	v_pk_mul_f32 v[66:67], v[66:67], v[118:119]
	v_pk_mul_f32 v[68:69], v[100:101], v[68:69]
	v_pk_mul_f32 v[70:71], v[102:103], v[70:71]
	v_pk_mul_f32 v[100:101], v[104:105], v[64:65]
	v_pk_mul_f32 v[102:103], v[106:107], v[66:67]
	v_cvt_pk_bf16_f32 v64, v68, v69
	v_cvt_pk_bf16_f32 v65, v70, v71
	v_cvt_pk_bf16_f32 v66, v100, v101
	v_cvt_pk_bf16_f32 v67, v102, v103
	global_store_dwordx4 v[94:95], v[64:67], off
	s_nop 1
	global_load_dwordx4 v[64:67], v[86:87], off
	v_rcp_f32_e32 v68, v127
	s_nop 0
	v_mul_f32_e32 v73, v73, v68
	v_rcp_f32_e32 v68, v126
	s_nop 0
	v_mul_f32_e32 v72, v72, v68
	v_rcp_f32_e32 v68, v129
	s_nop 0
	v_mul_f32_e32 v79, v79, v68
	global_load_dwordx4 v[68:71], v[82:83], off
	global_load_dwordx4 v[100:103], v[82:83], off offset:16
	v_rcp_f32_e32 v85, v131
	s_nop 0
	v_mul_f32_e32 v77, v77, v85
	v_rcp_f32_e32 v85, v130
	s_nop 0
	v_mul_f32_e32 v76, v76, v85
	v_rcp_f32_e32 v85, v133
	s_nop 0
	v_mul_f32_e32 v75, v75, v85
	v_rcp_f32_e32 v85, v132
	s_nop 0
	v_mul_f32_e32 v74, v74, v85
	v_rcp_f32_e32 v96, v128
	s_nop 0
	v_mul_f32_e32 v78, v78, v96
	s_addk_i32 s68, 0x200
	s_cmpk_lg_i32 s68, 0x800
	s_waitcnt vmcnt(2)
	v_lshlrev_b32_e32 v94, 16, v64
	v_and_b32_e32 v95, 0xffff0000, v64
	v_lshlrev_b32_e32 v64, 16, v65
	v_and_b32_e32 v65, 0xffff0000, v65
	v_pk_mul_f32 v[118:119], v[94:95], v[94:95]
	v_pk_mul_f32 v[116:117], v[64:65], v[64:65]
	v_add_f32_e32 v85, v118, v119
	v_lshlrev_b32_e32 v104, 16, v66
	v_and_b32_e32 v105, 0xffff0000, v66
	v_add_f32_e32 v85, v85, v116
	v_pk_mul_f32 v[108:109], v[104:105], v[104:105]
	v_add_f32_e32 v85, v117, v85
	v_lshlrev_b32_e32 v66, 16, v67
	v_and_b32_e32 v67, 0xffff0000, v67
	v_add_f32_e32 v85, v108, v85
	v_pk_mul_f32 v[106:107], v[66:67], v[66:67]
	v_add_f32_e32 v85, v109, v85
	v_add_f32_e32 v85, v106, v85
	v_add_f32_e32 v85, v107, v85
	ds_bpermute_b32 v93, v89, v85
	s_waitcnt lgkmcnt(0)
	v_add_f32_e32 v85, v85, v93
	ds_bpermute_b32 v93, v90, v85
	s_waitcnt lgkmcnt(0)
	v_add_f32_e32 v85, v85, v93
	ds_bpermute_b32 v93, v91, v85
	s_waitcnt lgkmcnt(0)
	v_add_f32_e32 v85, v85, v93
	ds_bpermute_b32 v93, v92, v85
	s_waitcnt lgkmcnt(0)
	v_add_f32_e32 v85, v85, v93
	v_fmamk_f32 v85, v85, 0x3c000000, v110
	v_mul_f32_e32 v93, 0x4b800000, v85
	v_cmp_gt_f32_e32 vcc, s60, v85
	s_nop 1
	s_nop 0
	v_cndmask_b32_e32 v85, v85, v93, vcc
	v_rsq_f32_e32 v85, v85
	s_nop 0
	v_mul_f32_e32 v93, 0x45800000, v85
	v_cndmask_b32_e32 v96, v85, v93, vcc
	v_pk_mul_f32 v[94:95], v[96:97], v[94:95] op_sel_hi:[0,1]
	v_pk_mul_f32 v[64:65], v[96:97], v[64:65] op_sel_hi:[0,1]
	v_pk_mul_f32 v[104:105], v[96:97], v[104:105] op_sel_hi:[0,1]
	v_pk_mul_f32 v[66:67], v[96:97], v[66:67] op_sel_hi:[0,1]
	s_waitcnt vmcnt(1)
	v_pk_mul_f32 v[68:69], v[68:69], v[94:95]
	v_pk_mul_f32 v[64:65], v[70:71], v[64:65]
	s_waitcnt vmcnt(0)
	v_pk_mul_f32 v[70:71], v[100:101], v[104:105]
	v_pk_mul_f32 v[66:67], v[102:103], v[66:67]
	v_pk_mul_f32 v[68:69], v[76:77], v[68:69]
	v_pk_mul_f32 v[76:77], v[78:79], v[64:65]
	v_pk_mul_f32 v[70:71], v[72:73], v[70:71]
	v_pk_mul_f32 v[72:73], v[74:75], v[66:67]
	v_cvt_pk_bf16_f32 v64, v68, v69
	v_cvt_pk_bf16_f32 v65, v76, v77
	v_cvt_pk_bf16_f32 v66, v70, v71
	v_cvt_pk_bf16_f32 v67, v72, v73
	global_store_dwordx4 v[86:87], v[64:67], off
	s_cbranch_scc1 .LBB0_380
	s_barrier

; __device__ __forceinline__ float bflo(unsigned v) { return __uint_as_float(v << 16); }
; __device__ __forceinline__ float bfhi(unsigned v) { return __uint_as_float(v & 0xffff0000u); }
; __device__ __forceinline__ float siluf_(float x) { return x / (1.f + __expf(-x)); }
; __device__ __forceinline__ uint4 pack8(float4 a, float4 b) { uint4 o; o.x = cvtpk(a.x, a.y); o.y = cvtpk(a.z, a.w); o.z = cvtpk(b.x, b.y); o.w = cvtpk(b.z, b.w); return o; }
; __device__ __forceinline__ void phase4(const Params& p, unsigned char* smem) {
;     ...
;       epilogue_rows(acc, m0, n0, smem, [&](int m, int n, float4 a, float4 b) {
;         uint4* ptr = (uint4*)(AQ + (size_t)tokrow_of(m) * 1024 + (n - 3072));
;         uint4 o = *ptr;
;         a.x = bflo(o.x) * siluf_(a.x); a.y = bfhi(o.x) * siluf_(a.y); a.z = bflo(o.y) * siluf_(a.z); a.w = bfhi(o.y) * siluf_(a.w);
;         b.x = bflo(o.z) * siluf_(b.x); b.y = bfhi(o.z) * siluf_(b.y); b.z = bflo(o.w) * siluf_(b.z); b.w = bfhi(o.w) * siluf_(b.w);
;         *ptr = pack8(a, b);
;       });
.LBB0_385:
	s_nop 0
	v_add_u32_e32 v0, s67, v9
	v_ashrrev_i32_e32 v2, 4, v0
	v_add_u32_e32 v3, 0x100, v0
	v_mad_u64_u32 v[0:1], s[4:5], v2, s56, v[8:9]
	v_add_u32_e32 v1, s66, v2
	v_ashrrev_i32_e32 v2, 4, v3
	v_ashrrev_i32_e32 v3, 13, v1
	v_and_b32_e32 v20, 0x1fff, v1
	ds_read_b128 v[12:15], v0
	ds_read_b128 v[16:19], v0 offset:16
	v_mad_u64_u32 v[0:1], s[4:5], v2, s56, v[8:9]
	v_add_u32_e32 v1, s66, v2
	v_mul_i32_i24_e32 v21, 0x2010, v3
	v_ashrrev_i32_e32 v22, 13, v1
	v_add3_u32 v20, v20, v21, 16
	v_and_b32_e32 v23, 0x1fff, v1
	v_mul_i32_i24_e32 v22, 0x2010, v22
	v_ashrrev_i32_e32 v21, 31, v20
	ds_read_b128 v[4:7], v0
	ds_read_b128 v[0:3], v0 offset:16
	v_add3_u32 v22, v23, v22, 16
	v_lshlrev_b64 v[20:21], 11, v[20:21]
	v_ashrrev_i32_e32 v23, 31, v22
	v_lshl_add_u64 v[20:21], v[10:11], 0, v[20:21]
	s_waitcnt lgkmcnt(3)
	v_mul_f32_e32 v25, 0xbfb8aa3b, v12
	v_lshlrev_b64 v[22:23], 11, v[22:23]
	v_add_co_u32_e32 v24, vcc, s61, v20
	v_exp_f32_e32 v26, v25
	v_lshl_add_u64 v[22:23], v[10:11], 0, v[22:23]
	v_addc_co_u32_e32 v25, vcc, -1, v21, vcc
	s_waitcnt lgkmcnt(1)
	v_mul_f32_e32 v20, 0xbfb8aa3b, v4
	v_add_co_u32_e32 v34, vcc, s61, v22
	v_exp_f32_e32 v36, v20
	s_nop 0
	v_addc_co_u32_e32 v35, vcc, -1, v23, vcc
	global_load_dwordx4 v[20:23], v[24:25], off offset:-2048
	v_mul_f32_e32 v27, 0xbfb8aa3b, v13
	v_mul_f32_e32 v32, 0xbfb8aa3b, v18
	v_mul_f32_e32 v33, 0xbfb8aa3b, v19
	v_exp_f32_e32 v27, v27
	v_mul_f32_e32 v28, 0xbfb8aa3b, v14
	v_mul_f32_e32 v29, 0xbfb8aa3b, v15
	v_exp_f32_e32 v32, v32
	v_exp_f32_e32 v33, v33
	v_exp_f32_e32 v28, v28
	v_exp_f32_e32 v29, v29
	v_mul_f32_e32 v30, 0xbfb8aa3b, v16
	v_mul_f32_e32 v31, 0xbfb8aa3b, v17
	v_exp_f32_e32 v30, v30
	v_exp_f32_e32 v31, v31
	v_pk_add_f32 v[26:27], v[26:27], 1.0 op_sel_hi:[1,0]
	v_pk_add_f32 v[32:33], v[32:33], 1.0 op_sel_hi:[1,0]
	v_pk_add_f32 v[28:29], v[28:29], 1.0 op_sel_hi:[1,0]
	v_pk_add_f32 v[30:31], v[30:31], 1.0 op_sel_hi:[1,0]
	s_waitcnt vmcnt(1)
	v_rcp_f32_e32 v44, v27
	s_nop 0
	v_mul_f32_e32 v13, v13, v44
	v_rcp_f32_e32 v27, v26
	s_nop 0
	v_mul_f32_e32 v12, v12, v27
	v_rcp_f32_e32 v26, v29
	s_nop 0
	v_mul_f32_e32 v15, v15, v26
	v_rcp_f32_e32 v26, v28
	s_nop 0
	v_mul_f32_e32 v14, v14, v26
	v_rcp_f32_e32 v26, v31
	s_nop 0
	v_mul_f32_e32 v17, v17, v26
	v_rcp_f32_e32 v26, v30
	s_nop 0
	v_mul_f32_e32 v16, v16, v26
	v_rcp_f32_e32 v26, v33
	s_nop 0
	v_mul_f32_e32 v19, v19, v26
	v_rcp_f32_e32 v26, v32
	s_nop 0
	v_mul_f32_e32 v18, v18, v26
	s_waitcnt vmcnt(0)
	v_lshlrev_b32_e32 v26, 16, v20
	v_and_b32_e32 v27, 0xffff0000, v20
	v_lshlrev_b32_e32 v20, 16, v21
	v_and_b32_e32 v21, 0xffff0000, v21
	v_lshlrev_b32_e32 v28, 16, v22
	v_and_b32_e32 v29, 0xffff0000, v22
	v_lshlrev_b32_e32 v22, 16, v23
	v_and_b32_e32 v23, 0xffff0000, v23
	v_pk_mul_f32 v[12:13], v[12:13], v[26:27]
	v_pk_mul_f32 v[14:15], v[14:15], v[20:21]
	v_pk_mul_f32 v[16:17], v[16:17], v[28:29]
	v_pk_mul_f32 v[18:19], v[18:19], v[22:23]
	v_cvt_pk_bf16_f32 v12, v12, v13
	v_cvt_pk_bf16_f32 v13, v14, v15
	v_cvt_pk_bf16_f32 v14, v16, v17
	v_cvt_pk_bf16_f32 v15, v18, v19
	global_store_dwordx4 v[24:25], v[12:15], off offset:-2048
	s_nop 1
	global_load_dwordx4 v[12:15], v[34:35], off offset:-2048
	v_mul_f32_e32 v37, 0xbfb8aa3b, v5
	s_waitcnt lgkmcnt(0)
	v_mul_f32_e32 v42, 0xbfb8aa3b, v2
	v_mul_f32_e32 v43, 0xbfb8aa3b, v3
	v_exp_f32_e32 v37, v37
	v_mul_f32_e32 v38, 0xbfb8aa3b, v6
	v_mul_f32_e32 v39, 0xbfb8aa3b, v7
	v_exp_f32_e32 v42, v42
	v_exp_f32_e32 v43, v43
	v_exp_f32_e32 v38, v38
	v_exp_f32_e32 v39, v39
	v_mul_f32_e32 v40, 0xbfb8aa3b, v0
	v_mul_f32_e32 v41, 0xbfb8aa3b, v1
	v_exp_f32_e32 v40, v40
	v_exp_f32_e32 v41, v41
	v_pk_add_f32 v[36:37], v[36:37], 1.0 op_sel_hi:[1,0]
	v_pk_add_f32 v[42:43], v[42:43], 1.0 op_sel_hi:[1,0]
	v_pk_add_f32 v[38:39], v[38:39], 1.0 op_sel_hi:[1,0]
	v_pk_add_f32 v[40:41], v[40:41], 1.0 op_sel_hi:[1,0]
	v_rcp_f32_e32 v16, v37
	s_nop 0
	v_mul_f32_e32 v5, v5, v16
	v_rcp_f32_e32 v16, v36
	s_nop 0
	v_mul_f32_e32 v4, v4, v16
	v_rcp_f32_e32 v16, v39
	s_nop 0
	v_mul_f32_e32 v7, v7, v16
	v_rcp_f32_e32 v16, v38
	s_nop 0
	v_mul_f32_e32 v6, v6, v16
	v_rcp_f32_e32 v16, v41
	s_nop 0
	v_mul_f32_e32 v1, v1, v16
	v_rcp_f32_e32 v16, v40
	s_nop 0
	v_mul_f32_e32 v0, v0, v16
	v_rcp_f32_e32 v16, v43
	s_nop 0
	v_mul_f32_e32 v3, v3, v16
	v_rcp_f32_e32 v16, v42
	s_nop 0
	v_mul_f32_e32 v2, v2, v16
	s_waitcnt vmcnt(0)
	v_lshlrev_b32_e32 v16, 16, v12
	v_and_b32_e32 v17, 0xffff0000, v12
	v_lshlrev_b32_e32 v12, 16, v13
	v_and_b32_e32 v13, 0xffff0000, v13
	v_lshlrev_b32_e32 v18, 16, v14
	v_and_b32_e32 v19, 0xffff0000, v14
	v_lshlrev_b32_e32 v14, 16, v15
	v_and_b32_e32 v15, 0xffff0000, v15
	s_addk_i32 s67, 0x200
	v_pk_mul_f32 v[4:5], v[4:5], v[16:17]
	v_pk_mul_f32 v[6:7], v[6:7], v[12:13]
	v_pk_mul_f32 v[12:13], v[0:1], v[18:19]
	v_pk_mul_f32 v[14:15], v[2:3], v[14:15]
	s_cmpk_lg_i32 s67, 0x800
	v_cvt_pk_bf16_f32 v0, v4, v5
	v_cvt_pk_bf16_f32 v1, v6, v7
	v_cvt_pk_bf16_f32 v2, v12, v13
	v_cvt_pk_bf16_f32 v3, v14, v15
	global_store_dwordx4 v[34:35], v[0:3], off offset:-2048
	s_cbranch_scc1 .LBB0_385
	s_barrier
	s_branch .LBB0_353
